# P6 cross-attention: next-chunk K/V global loads hoisted to the start of each MFMA block (fresh VGPRs)
# speedup vs baseline: 1.0006x; 1.0006x over previous
; __device__ __forceinline__ int crow(int r,int hi){return (r&3)+8*(r>>2)+4*hi;}
; #define XLAS __attribute__((address_space(3)))
; __device__ __forceinline__ int crow(int r, int hi) { return (r & 3) + 8 * (r >> 2) + 4 * hi; }
; #define X_LOADV(c)  do { _Pragma("unroll") for (int i_ = 0; i_ < 4; ++i_) st[i_] = *(const u32x4*)(Vg + (size_t)(c) * 64 * 2048 + i_ * 64); } while (0)
; __device__ __forceinline__ void unit(int b, int h, int qblk, const bf16_t* __restrict__ CQ, const bf16_t* __restrict__ CK, const bf16_t* __restrict__ CVT, bf16_t* __restrict__ CO, XLAS unsigned char* lds, const int wv) {
;     ...
;     float rli[16];
; #pragma unroll
;     for (int r = 0; r < 16; ++r) rli[r] = __builtin_amdgcn_rcpf(wsf[crow(r, hi)]);
;     XLAS bf16_t* stg = (XLAS bf16_t*)(lds + X_OST) + wid * 2048;
;     bf16_t* Ow = CO + qrow0 * 1024 + h * 256;
; #pragma unroll
;     for (int c = 0; c < 4; ++c) {
;         const int buf = (c & 1) ? XB1 : XB0, nbuf = (c & 1) ? XB0 : XB1;
;         if (c < 3) X_LOADV(c + 1);
;         f32x16 o[2]; o[0] = f32x16{}; o[1] = f32x16{};
; #pragma unroll
;         for (int j = 0; j < 16; ++j)
; #pragma unroll
;             for (int dt = 0; dt < 2; ++dt) {
;                 const bf16x8 vf = *(const XLAS bf16x8*)(lds + buf + voff + dt * 512 + j * 2048);
;                 o[dt] = __builtin_amdgcn_mfma_f32_32x32x16_bf16(__builtin_bit_cast(bf16x8, pw[j]), vf, o[dt], 0, 0, 0);
;             }
.LBB0_1144:
	s_or_b64 exec, exec, s[14:15]
	s_mov_b32 s30, s23
	s_mov_b32 s31, 0
	v_lshl_add_u64 v[242:243], v[144:145], 0, s[30:31]
	global_load_dwordx4 v[226:229], v[242:243], off
	global_load_dwordx4 v[230:233], v[242:243], off offset:128
	global_load_dwordx4 v[234:237], v[242:243], off offset:256
	global_load_dwordx4 v[238:241], v[242:243], off offset:384
	v_lshlrev_b32_e32 v0, 4, v191
	s_waitcnt lgkmcnt(0)
	v_lshlrev_b32_e32 v1, 10, v192
	s_waitcnt lgkmcnt(0)
	v_add3_u32 v104, 0, v1, v0
	ds_read_b128 v[0:3], v104
	ds_read_b128 v[4:7], v104 offset:512
	ds_read_b128 v[96:99], v104 offset:2048
	ds_read_b128 v[100:103], v104 offset:2560
	s_waitcnt lgkmcnt(3)
	v_mfma_f32_32x32x16_bf16 v[16:31], v[92:95], v[0:3], 0
	v_lshl_add_u32 v105, v192, 4, s17
	s_add_i32 s4, s4, 0x10800
	s_lshl_b64 s[12:13], s[12:13], 11
	s_add_u32 s12, s18, s12
	s_addc_u32 s13, s19, s13
	s_lshl_b32 s14, s16, 1
	s_add_u32 s12, s12, s14
	s_waitcnt lgkmcnt(2)
	v_mfma_f32_32x32x16_bf16 v[0:15], v[92:95], v[4:7], 0
	s_addc_u32 s13, s13, 0
	s_add_i32 s2, s2, 1
	s_addk_i32 s21, 0x100
	s_cmp_lt_i32 s2, s3
	s_waitcnt lgkmcnt(1)
	v_mfma_f32_32x32x16_bf16 v[16:31], v[88:91], v[96:99], v[16:31]
	s_waitcnt lgkmcnt(0)
	v_mfma_f32_32x32x16_bf16 v[0:15], v[88:91], v[100:103], v[0:15]
	ds_read_b128 v[96:99], v104 offset:4096
	ds_read_b128 v[100:103], v104 offset:4608
	s_waitcnt lgkmcnt(1)
	v_mfma_f32_32x32x16_bf16 v[16:31], v[84:87], v[96:99], v[16:31]
	s_waitcnt lgkmcnt(0)
	v_mfma_f32_32x32x16_bf16 v[0:15], v[84:87], v[100:103], v[0:15]
	ds_read_b128 v[96:99], v104 offset:6144
	ds_read_b128 v[100:103], v104 offset:6656
	s_waitcnt lgkmcnt(1)
	v_mfma_f32_32x32x16_bf16 v[16:31], v[80:83], v[96:99], v[16:31]
	s_waitcnt lgkmcnt(0)
	v_mfma_f32_32x32x16_bf16 v[0:15], v[80:83], v[100:103], v[0:15]
	ds_read_b128 v[96:99], v104 offset:8192
	ds_read_b128 v[100:103], v104 offset:8704
	s_waitcnt lgkmcnt(1)
	v_mfma_f32_32x32x16_bf16 v[16:31], v[76:79], v[96:99], v[16:31]
	s_waitcnt lgkmcnt(0)
	v_mfma_f32_32x32x16_bf16 v[0:15], v[76:79], v[100:103], v[0:15]
	ds_read_b128 v[96:99], v104 offset:10240
	ds_read_b128 v[100:103], v104 offset:10752
	s_waitcnt lgkmcnt(1)
	v_mfma_f32_32x32x16_bf16 v[16:31], v[72:75], v[96:99], v[16:31]
	s_waitcnt lgkmcnt(0)
	v_mfma_f32_32x32x16_bf16 v[0:15], v[72:75], v[100:103], v[0:15]
	ds_read_b128 v[96:99], v104 offset:12288
	ds_read_b128 v[100:103], v104 offset:12800
	s_waitcnt lgkmcnt(1)
	v_mfma_f32_32x32x16_bf16 v[16:31], v[68:71], v[96:99], v[16:31]
	s_waitcnt lgkmcnt(0)
	v_mfma_f32_32x32x16_bf16 v[0:15], v[68:71], v[100:103], v[0:15]
	ds_read_b128 v[96:99], v104 offset:14336
	ds_read_b128 v[100:103], v104 offset:14848
	s_waitcnt lgkmcnt(1)
	v_mfma_f32_32x32x16_bf16 v[16:31], v[64:67], v[96:99], v[16:31]
	s_waitcnt lgkmcnt(0)
	v_mfma_f32_32x32x16_bf16 v[0:15], v[64:67], v[100:103], v[0:15]
	ds_read_b128 v[96:99], v104 offset:16384
	ds_read_b128 v[100:103], v104 offset:16896
	s_waitcnt lgkmcnt(1)
	v_mfma_f32_32x32x16_bf16 v[16:31], v[60:63], v[96:99], v[16:31]
	s_waitcnt lgkmcnt(0)
	v_mfma_f32_32x32x16_bf16 v[0:15], v[60:63], v[100:103], v[0:15]
	ds_read_b128 v[96:99], v104 offset:18432
	ds_read_b128 v[100:103], v104 offset:18944
	s_waitcnt lgkmcnt(1)
	v_mfma_f32_32x32x16_bf16 v[16:31], v[56:59], v[96:99], v[16:31]
	s_waitcnt lgkmcnt(0)
	v_mfma_f32_32x32x16_bf16 v[0:15], v[56:59], v[100:103], v[0:15]
	ds_read_b128 v[96:99], v104 offset:20480
	ds_read_b128 v[100:103], v104 offset:20992
	s_waitcnt lgkmcnt(1)
	v_mfma_f32_32x32x16_bf16 v[16:31], v[52:55], v[96:99], v[16:31]
	s_waitcnt lgkmcnt(0)
	v_mfma_f32_32x32x16_bf16 v[0:15], v[52:55], v[100:103], v[0:15]
	ds_read_b128 v[96:99], v104 offset:22528
	ds_read_b128 v[100:103], v104 offset:23040
	s_waitcnt lgkmcnt(1)
	v_mfma_f32_32x32x16_bf16 v[16:31], v[48:51], v[96:99], v[16:31]
	ds_read_b128 v[96:99], v104 offset:24576
	s_waitcnt lgkmcnt(1)
	v_mfma_f32_32x32x16_bf16 v[0:15], v[48:51], v[100:103], v[0:15]
	ds_read_b128 v[100:103], v104 offset:25088
	s_waitcnt lgkmcnt(1)
	v_mfma_f32_32x32x16_bf16 v[16:31], v[44:47], v[96:99], v[16:31]
	ds_read_b128 v[96:99], v105
	ds_read_b128 v[106:109], v105 offset:32
	ds_read_b128 v[122:125], v104 offset:27136
	s_waitcnt lgkmcnt(2)
	v_rcp_f32_e32 v121, v96
	v_rcp_f32_e32 v120, v97
	v_rcp_f32_e32 v119, v98
	v_mfma_f32_32x32x16_bf16 v[0:15], v[44:47], v[100:103], v[0:15]
	v_rcp_f32_e32 v118, v99
	ds_read_b128 v[96:99], v104 offset:26624
	ds_read_b128 v[100:103], v105 offset:64
	s_waitcnt lgkmcnt(3)
	v_rcp_f32_e32 v117, v106
	v_rcp_f32_e32 v116, v107
	v_rcp_f32_e32 v115, v108
	v_rcp_f32_e32 v113, v109
	s_waitcnt lgkmcnt(1)
	v_mfma_f32_32x32x16_bf16 v[16:31], v[40:43], v[96:99], v[16:31]
	ds_read_b128 v[96:99], v105 offset:96
	s_waitcnt lgkmcnt(1)
	v_rcp_f32_e32 v114, v100
	v_rcp_f32_e32 v112, v101
	v_rcp_f32_e32 v111, v102
	v_rcp_f32_e32 v110, v103
	s_waitcnt lgkmcnt(0)
	v_rcp_f32_e32 v108, v96
	v_rcp_f32_e32 v107, v97
	v_mfma_f32_32x32x16_bf16 v[0:15], v[40:43], v[122:125], v[0:15]
	v_rcp_f32_e32 v106, v98
	v_rcp_f32_e32 v105, v99
	ds_read_b128 v[96:99], v104 offset:28672
	ds_read_b128 v[100:103], v104 offset:29184
	v_lshrrev_b32_e32 v125, 3, v190
	s_waitcnt lgkmcnt(1)
	v_mfma_f32_32x32x16_bf16 v[16:31], v[36:39], v[96:99], v[16:31]
	v_lshlrev_b32_e32 v96, 9, v192
	v_lshlrev_b32_e32 v97, 1, v191
	v_add3_u32 v109, s4, v96, v97
	ds_read_b128 v[96:99], v104 offset:30720
	s_waitcnt lgkmcnt(1)
	v_mfma_f32_32x32x16_bf16 v[0:15], v[36:39], v[100:103], v[0:15]
	v_lshlrev_b32_e32 v100, 4, v189
	v_and_b32_e32 v176, 0x70, v100
	ds_read_b128 v[100:103], v104 offset:31232
	v_add_u32_e32 v147, s4, v176
	v_lshl_add_u32 v122, v125, 7, v147
	v_lshl_add_u64 v[142:143], s[12:13], 0, v[176:177]
	v_lshlrev_b32_e32 v176, 11, v125
	s_waitcnt lgkmcnt(1)
; __device__ __forceinline__ int crow(int r,int hi){return (r&3)+8*(r>>2)+4*hi;}
; #define XLAS __attribute__((address_space(3)))
; __device__ __forceinline__ int crow(int r, int hi) { return (r & 3) + 8 * (r >> 2) + 4 * hi; }
; __device__ __forceinline__ unsigned pk(float lo, float hi) { return pg8::cvt_pk_bf16(lo, hi); }
; #define X_LOADV(c)  do { _Pragma("unroll") for (int i_ = 0; i_ < 4; ++i_) st[i_] = *(const u32x4*)(Vg + (size_t)(c) * 64 * 2048 + i_ * 64); } while (0)
; #define X_STOREV(buf) do { _Pragma("unroll") for (int i_ = 0; i_ < 4; ++i_) *(XLAS u32x4*)(lds + (buf) + (wid + 8 * i_) * 1024 + lane * 16) = st[i_]; } while (0)
; __device__ __forceinline__ void unit(int b, int h, int qblk, const bf16_t* __restrict__ CQ, const bf16_t* __restrict__ CK, const bf16_t* __restrict__ CVT, bf16_t* __restrict__ CO, XLAS unsigned char* lds, const int wv) {
;     ...
;         if (c < 3) X_LOADV(c + 1);
;         f32x16 o[2]; o[0] = f32x16{}; o[1] = f32x16{};
; #pragma unroll
;         for (int j = 0; j < 16; ++j)
; #pragma unroll
;             for (int dt = 0; dt < 2; ++dt) {
;                 const bf16x8 vf = *(const XLAS bf16x8*)(lds + buf + voff + dt * 512 + j * 2048);
;                 o[dt] = __builtin_amdgcn_mfma_f32_32x32x16_bf16(__builtin_bit_cast(bf16x8, pw[j]), vf, o[dt], 0, 0, 0);
;             }
; #pragma unroll
;         for (int r = 0; r < 16; ++r) { const int orow = crow(r, hi);
; #pragma unroll
;             for (int dt = 0; dt < 2; ++dt) { const unsigned w = pk(o[dt][r] * rli[r], 0.f); stg[orow * 64 + dt * 32 + r32] = (bf16_t)(w & 0xffffu); } }
;         asm volatile("s_waitcnt lgkmcnt(0)" ::: "memory");
; #pragma unroll
;         for (int i = 0; i < 4; ++i) { const int row = i * 8 + (lane >> 3), ch = lane & 7; const u32x4 v = *(const XLAS u32x4*)(stg + row * 64 + ch * 8); *(u32x4*)(Ow + (size_t)row * 1024 + c * 64 + ch * 8) = v; }
;         asm volatile("s_waitcnt lgkmcnt(0)" ::: "memory");
;         if (c < 3) X_STOREV(nbuf);
;         __syncthreads();
	v_mfma_f32_32x32x16_bf16 v[16:31], v[32:35], v[96:99], v[16:31]
	v_add_co_u32_e32 v96, vcc, s23, v144
	s_nop 1
	v_addc_co_u32_e32 v97, vcc, 0, v145, vcc
	v_lshl_add_u64 v[96:97], v[142:143], 0, v[176:177]
	s_waitcnt lgkmcnt(0)
	v_mfma_f32_32x32x16_bf16 v[0:15], v[32:35], v[100:103], v[0:15]
	s_nop 0
	v_mul_f32_e32 v16, v121, v16
	v_cvt_pk_bf16_f32 v16, v16, v177
	ds_write_b16 v109, v16
	s_nop 8
	v_mul_f32_e32 v0, v121, v0
	v_cvt_pk_bf16_f32 v0, v0, v177
	ds_write_b16 v109, v0 offset:64
	v_mul_f32_e32 v0, v120, v17
	v_cvt_pk_bf16_f32 v0, v0, v177
	ds_write_b16 v109, v0 offset:128
	v_mul_f32_e32 v0, v120, v1
	v_cvt_pk_bf16_f32 v0, v0, v177
	ds_write_b16 v109, v0 offset:192
	v_mul_f32_e32 v0, v119, v18
	v_cvt_pk_bf16_f32 v0, v0, v177
	ds_write_b16 v109, v0 offset:256
	v_mul_f32_e32 v0, v119, v2
	v_cvt_pk_bf16_f32 v0, v0, v177
	ds_write_b16 v109, v0 offset:320
	v_mul_f32_e32 v0, v118, v19
	v_cvt_pk_bf16_f32 v0, v0, v177
	ds_write_b16 v109, v0 offset:384
	v_mul_f32_e32 v0, v118, v3
	v_cvt_pk_bf16_f32 v0, v0, v177
	ds_write_b16 v109, v0 offset:448
	v_mul_f32_e32 v0, v117, v20
	v_cvt_pk_bf16_f32 v0, v0, v177
	ds_write_b16 v109, v0 offset:1024
	v_mul_f32_e32 v0, v117, v4
	v_cvt_pk_bf16_f32 v0, v0, v177
	ds_write_b16 v109, v0 offset:1088
	v_mul_f32_e32 v0, v116, v21
	v_cvt_pk_bf16_f32 v0, v0, v177
	ds_write_b16 v109, v0 offset:1152
	v_mul_f32_e32 v0, v116, v5
	v_cvt_pk_bf16_f32 v0, v0, v177
	ds_write_b16 v109, v0 offset:1216
	v_mul_f32_e32 v0, v115, v22
	v_cvt_pk_bf16_f32 v0, v0, v177
	ds_write_b16 v109, v0 offset:1280
	v_mul_f32_e32 v0, v115, v6
	v_cvt_pk_bf16_f32 v0, v0, v177
	ds_write_b16 v109, v0 offset:1344
	v_mul_f32_e32 v0, v113, v23
	v_cvt_pk_bf16_f32 v0, v0, v177
	ds_write_b16 v109, v0 offset:1408
	v_mul_f32_e32 v0, v113, v7
	v_cvt_pk_bf16_f32 v0, v0, v177
	ds_write_b16 v109, v0 offset:1472
	v_mul_f32_e32 v0, v114, v24
	v_cvt_pk_bf16_f32 v0, v0, v177
	ds_write_b16 v109, v0 offset:2048
	v_mul_f32_e32 v0, v114, v8
	v_cvt_pk_bf16_f32 v0, v0, v177
	ds_write_b16 v109, v0 offset:2112
	v_mul_f32_e32 v0, v112, v25
	v_cvt_pk_bf16_f32 v0, v0, v177
	ds_write_b16 v109, v0 offset:2176
	v_mul_f32_e32 v0, v112, v9
	v_cvt_pk_bf16_f32 v0, v0, v177
	ds_write_b16 v109, v0 offset:2240
	v_mul_f32_e32 v0, v111, v26
	v_cvt_pk_bf16_f32 v0, v0, v177
	ds_write_b16 v109, v0 offset:2304
	v_mul_f32_e32 v0, v111, v10
	v_cvt_pk_bf16_f32 v0, v0, v177
	ds_write_b16 v109, v0 offset:2368
	v_mul_f32_e32 v0, v110, v27
	v_cvt_pk_bf16_f32 v0, v0, v177
	ds_write_b16 v109, v0 offset:2432
	v_mul_f32_e32 v0, v110, v11
	v_cvt_pk_bf16_f32 v0, v0, v177
	ds_write_b16 v109, v0 offset:2496
	v_mul_f32_e32 v0, v108, v28
	v_cvt_pk_bf16_f32 v0, v0, v177
	ds_write_b16 v109, v0 offset:3072
	v_mul_f32_e32 v0, v108, v12
	v_cvt_pk_bf16_f32 v0, v0, v177
	ds_write_b16 v109, v0 offset:3136
	v_mul_f32_e32 v0, v107, v29
	v_cvt_pk_bf16_f32 v0, v0, v177
	ds_write_b16 v109, v0 offset:3200
	v_mul_f32_e32 v0, v107, v13
	v_cvt_pk_bf16_f32 v0, v0, v177
	ds_write_b16 v109, v0 offset:3264
	v_mul_f32_e32 v0, v106, v30
	v_cvt_pk_bf16_f32 v0, v0, v177
	ds_write_b16 v109, v0 offset:3328
	v_mul_f32_e32 v0, v106, v14
	v_cvt_pk_bf16_f32 v0, v0, v177
	ds_write_b16 v109, v0 offset:3392
	v_mul_f32_e32 v0, v105, v31
	v_cvt_pk_bf16_f32 v0, v0, v177
	ds_write_b16 v109, v0 offset:3456
	v_mul_f32_e32 v0, v105, v15
	v_cvt_pk_bf16_f32 v0, v0, v177
	ds_write_b16 v109, v0 offset:3520
	v_or_b32_e32 v8, 8, v125
	s_waitcnt lgkmcnt(0)
	v_lshl_add_u32 v123, v8, 7, v147
	ds_read_b128 v[0:3], v122
	ds_read_b128 v[4:7], v123
	v_lshlrev_b32_e32 v176, 11, v8
	v_lshl_add_u64 v[98:99], v[142:143], 0, v[176:177]
	v_or_b32_e32 v8, 24, v125
	s_waitcnt lgkmcnt(1)
	global_store_dwordx4 v[96:97], v[0:3], off
	s_waitcnt lgkmcnt(0)
	global_store_dwordx4 v[98:99], v[4:7], off
	s_nop 1
	v_or_b32_e32 v4, 16, v125
	v_lshl_add_u32 v124, v4, 7, v147
	v_lshl_add_u32 v125, v8, 7, v147
	ds_read_b128 v[0:3], v124
	v_lshlrev_b32_e32 v176, 11, v4
	ds_read_b128 v[4:7], v125
	v_lshl_add_u64 v[100:101], v[142:143], 0, v[176:177]
	v_lshlrev_b32_e32 v176, 11, v8
	v_lshl_add_u64 v[102:103], v[142:143], 0, v[176:177]
	s_waitcnt lgkmcnt(1)
	global_store_dwordx4 v[100:101], v[0:3], off
	s_waitcnt lgkmcnt(0)
	global_store_dwordx4 v[102:103], v[4:7], off
	s_waitcnt lgkmcnt(0)
	s_waitcnt vmcnt(7)
	ds_write_b128 v146, v[226:229] offset:32768
	s_waitcnt vmcnt(6)
	ds_write_b128 v146, v[230:233] offset:40960
	s_waitcnt vmcnt(5)
	ds_write_b128 v146, v[234:237] offset:49152
	s_waitcnt vmcnt(4)
	ds_write_b128 v146, v[238:241] offset:57344
	s_waitcnt lgkmcnt(0)
	s_barrier
; #define XLAS __attribute__((address_space(3)))
; #define X_LOADV(c)  do { _Pragma("unroll") for (int i_ = 0; i_ < 4; ++i_) st[i_] = *(const u32x4*)(Vg + (size_t)(c) * 64 * 2048 + i_ * 64); } while (0)
; __device__ __forceinline__ void unit(int b, int h, int qblk, const bf16_t* __restrict__ CQ, const bf16_t* __restrict__ CK, const bf16_t* __restrict__ CVT, bf16_t* __restrict__ CO, XLAS unsigned char* lds, const int wv) {
;     ...
;     for (int c = 0; c < 4; ++c) {
;         const int buf = (c & 1) ? XB1 : XB0, nbuf = (c & 1) ? XB0 : XB1;
;         if (c < 3) X_LOADV(c + 1);
;         f32x16 o[2]; o[0] = f32x16{}; o[1] = f32x16{};
; #pragma unroll
;         for (int j = 0; j < 16; ++j)
; #pragma unroll
;             for (int dt = 0; dt < 2; ++dt) {
;                 const bf16x8 vf = *(const XLAS bf16x8*)(lds + buf + voff + dt * 512 + j * 2048);
;                 o[dt] = __builtin_amdgcn_mfma_f32_32x32x16_bf16(__builtin_bit_cast(bf16x8, pw[j]), vf, o[dt], 0, 0, 0);
;             }
	ds_read_b128 v[0:3], v104 offset:32768
	ds_read_b128 v[4:7], v104 offset:33280
	s_waitcnt lgkmcnt(1)
	v_mfma_f32_32x32x16_bf16 v[16:31], v[92:95], v[0:3], 0
	ds_read_b128 v[126:129], v104 offset:34816
	ds_read_b128 v[130:133], v104 offset:35328
	v_add_co_u32_e32 v142, vcc, s25, v144
	s_nop 1
	v_addc_co_u32_e32 v143, vcc, 0, v145, vcc
	global_load_dwordx4 v[226:229], v[142:143], off
	global_load_dwordx4 v[230:233], v[142:143], off offset:128
	global_load_dwordx4 v[234:237], v[142:143], off offset:256
	global_load_dwordx4 v[238:241], v[142:143], off offset:384
	s_waitcnt lgkmcnt(2)
	v_mfma_f32_32x32x16_bf16 v[0:15], v[92:95], v[4:7], 0
	s_waitcnt lgkmcnt(1)
	v_mfma_f32_32x32x16_bf16 v[16:31], v[88:91], v[126:129], v[16:31]
	s_waitcnt lgkmcnt(0)
	v_mfma_f32_32x32x16_bf16 v[0:15], v[88:91], v[130:133], v[0:15]
	ds_read_b128 v[126:129], v104 offset:36864
	ds_read_b128 v[130:133], v104 offset:37376
	s_waitcnt lgkmcnt(1)
	v_mfma_f32_32x32x16_bf16 v[16:31], v[84:87], v[126:129], v[16:31]
	s_waitcnt lgkmcnt(0)
	v_mfma_f32_32x32x16_bf16 v[0:15], v[84:87], v[130:133], v[0:15]
	ds_read_b128 v[126:129], v104 offset:38912
	ds_read_b128 v[130:133], v104 offset:39424
	s_waitcnt lgkmcnt(1)
	v_mfma_f32_32x32x16_bf16 v[16:31], v[80:83], v[126:129], v[16:31]
	s_waitcnt lgkmcnt(0)
	v_mfma_f32_32x32x16_bf16 v[0:15], v[80:83], v[130:133], v[0:15]
	ds_read_b128 v[126:129], v104 offset:40960
	ds_read_b128 v[130:133], v104 offset:41472
	s_waitcnt lgkmcnt(1)
	v_mfma_f32_32x32x16_bf16 v[16:31], v[76:79], v[126:129], v[16:31]
	s_waitcnt lgkmcnt(0)
	v_mfma_f32_32x32x16_bf16 v[0:15], v[76:79], v[130:133], v[0:15]
	ds_read_b128 v[126:129], v104 offset:43008
	ds_read_b128 v[130:133], v104 offset:43520
	s_waitcnt lgkmcnt(1)
	v_mfma_f32_32x32x16_bf16 v[16:31], v[72:75], v[126:129], v[16:31]
	s_waitcnt lgkmcnt(0)
	v_mfma_f32_32x32x16_bf16 v[0:15], v[72:75], v[130:133], v[0:15]
	ds_read_b128 v[126:129], v104 offset:45056
	ds_read_b128 v[130:133], v104 offset:45568
	s_waitcnt lgkmcnt(1)
	v_mfma_f32_32x32x16_bf16 v[16:31], v[68:71], v[126:129], v[16:31]
	s_waitcnt lgkmcnt(0)
	v_mfma_f32_32x32x16_bf16 v[0:15], v[68:71], v[130:133], v[0:15]
	ds_read_b128 v[126:129], v104 offset:47104
	ds_read_b128 v[130:133], v104 offset:47616
	s_waitcnt lgkmcnt(1)
	v_mfma_f32_32x32x16_bf16 v[16:31], v[64:67], v[126:129], v[16:31]
	s_waitcnt lgkmcnt(0)
	v_mfma_f32_32x32x16_bf16 v[0:15], v[64:67], v[130:133], v[0:15]
	ds_read_b128 v[126:129], v104 offset:49152
	ds_read_b128 v[130:133], v104 offset:49664
	s_waitcnt lgkmcnt(1)
	v_mfma_f32_32x32x16_bf16 v[16:31], v[60:63], v[126:129], v[16:31]
	s_waitcnt lgkmcnt(0)
	v_mfma_f32_32x32x16_bf16 v[0:15], v[60:63], v[130:133], v[0:15]
	ds_read_b128 v[126:129], v104 offset:51200
	ds_read_b128 v[130:133], v104 offset:51712
	s_waitcnt lgkmcnt(1)
	v_mfma_f32_32x32x16_bf16 v[16:31], v[56:59], v[126:129], v[16:31]
	s_waitcnt lgkmcnt(0)
	v_mfma_f32_32x32x16_bf16 v[0:15], v[56:59], v[130:133], v[0:15]
	ds_read_b128 v[126:129], v104 offset:53248
	ds_read_b128 v[130:133], v104 offset:53760
	s_waitcnt lgkmcnt(1)
	v_mfma_f32_32x32x16_bf16 v[16:31], v[52:55], v[126:129], v[16:31]
	s_waitcnt lgkmcnt(0)
	v_mfma_f32_32x32x16_bf16 v[0:15], v[52:55], v[130:133], v[0:15]
	ds_read_b128 v[126:129], v104 offset:55296
	ds_read_b128 v[130:133], v104 offset:55808
	s_waitcnt lgkmcnt(1)
	v_mfma_f32_32x32x16_bf16 v[16:31], v[48:51], v[126:129], v[16:31]
	s_waitcnt lgkmcnt(0)
	v_mfma_f32_32x32x16_bf16 v[0:15], v[48:51], v[130:133], v[0:15]
	ds_read_b128 v[126:129], v104 offset:57344
	ds_read_b128 v[130:133], v104 offset:57856
	s_waitcnt lgkmcnt(1)
	v_mfma_f32_32x32x16_bf16 v[16:31], v[44:47], v[126:129], v[16:31]
	s_waitcnt lgkmcnt(0)
	v_mfma_f32_32x32x16_bf16 v[0:15], v[44:47], v[130:133], v[0:15]
	ds_read_b128 v[126:129], v104 offset:59392
	ds_read_b128 v[130:133], v104 offset:59904
	s_waitcnt lgkmcnt(1)
	v_mfma_f32_32x32x16_bf16 v[16:31], v[40:43], v[126:129], v[16:31]
	s_waitcnt lgkmcnt(0)
	v_mfma_f32_32x32x16_bf16 v[0:15], v[40:43], v[130:133], v[0:15]
	ds_read_b128 v[126:129], v104 offset:61440
	ds_read_b128 v[130:133], v104 offset:61952
	s_waitcnt lgkmcnt(1)
	v_mfma_f32_32x32x16_bf16 v[16:31], v[36:39], v[126:129], v[16:31]
	s_waitcnt lgkmcnt(0)
	v_mfma_f32_32x32x16_bf16 v[0:15], v[36:39], v[130:133], v[0:15]
	ds_read_b128 v[126:129], v104 offset:63488
	ds_read_b128 v[130:133], v104 offset:64000
	s_waitcnt lgkmcnt(1)
	v_mfma_f32_32x32x16_bf16 v[16:31], v[32:35], v[126:129], v[16:31]
	v_add_co_u32_e32 v142, vcc, s26, v144
	s_nop 6
	v_mul_f32_e32 v16, v121, v16
	s_waitcnt lgkmcnt(0)
; __device__ __forceinline__ int crow(int r,int hi){return (r&3)+8*(r>>2)+4*hi;}
; #define XLAS __attribute__((address_space(3)))
; __device__ __forceinline__ int crow(int r, int hi) { return (r & 3) + 8 * (r >> 2) + 4 * hi; }
; __device__ __forceinline__ unsigned pk(float lo, float hi) { return pg8::cvt_pk_bf16(lo, hi); }
; #define X_LOADV(c)  do { _Pragma("unroll") for (int i_ = 0; i_ < 4; ++i_) st[i_] = *(const u32x4*)(Vg + (size_t)(c) * 64 * 2048 + i_ * 64); } while (0)
; #define X_STOREV(buf) do { _Pragma("unroll") for (int i_ = 0; i_ < 4; ++i_) *(XLAS u32x4*)(lds + (buf) + (wid + 8 * i_) * 1024 + lane * 16) = st[i_]; } while (0)
; __device__ __forceinline__ void unit(int b, int h, int qblk, const bf16_t* __restrict__ CQ, const bf16_t* __restrict__ CK, const bf16_t* __restrict__ CVT, bf16_t* __restrict__ CO, XLAS unsigned char* lds, const int wv) {
;     ...
;     for (int c = 0; c < 4; ++c) {
;         const int buf = (c & 1) ? XB1 : XB0, nbuf = (c & 1) ? XB0 : XB1;
;         if (c < 3) X_LOADV(c + 1);
;         f32x16 o[2]; o[0] = f32x16{}; o[1] = f32x16{};
; #pragma unroll
;         for (int j = 0; j < 16; ++j)
; #pragma unroll
;             for (int dt = 0; dt < 2; ++dt) {
;                 const bf16x8 vf = *(const XLAS bf16x8*)(lds + buf + voff + dt * 512 + j * 2048);
;                 o[dt] = __builtin_amdgcn_mfma_f32_32x32x16_bf16(__builtin_bit_cast(bf16x8, pw[j]), vf, o[dt], 0, 0, 0);
;             }
; #pragma unroll
;         for (int r = 0; r < 16; ++r) { const int orow = crow(r, hi);
; #pragma unroll
;             for (int dt = 0; dt < 2; ++dt) { const unsigned w = pk(o[dt][r] * rli[r], 0.f); stg[orow * 64 + dt * 32 + r32] = (bf16_t)(w & 0xffffu); } }
;         asm volatile("s_waitcnt lgkmcnt(0)" ::: "memory");
; #pragma unroll
;         for (int i = 0; i < 4; ++i) { const int row = i * 8 + (lane >> 3), ch = lane & 7; const u32x4 v = *(const XLAS u32x4*)(stg + row * 64 + ch * 8); *(u32x4*)(Ow + (size_t)row * 1024 + c * 64 + ch * 8) = v; }
;         asm volatile("s_waitcnt lgkmcnt(0)" ::: "memory");
;         if (c < 3) X_STOREV(nbuf);
;         __syncthreads();
	v_mfma_f32_32x32x16_bf16 v[0:15], v[32:35], v[130:133], v[0:15]
	v_cvt_pk_bf16_f32 v16, v16, v177
	ds_write_b16 v109, v16
	v_addc_co_u32_e32 v143, vcc, 0, v145, vcc
	s_nop 9
	v_mul_f32_e32 v0, v121, v0
	v_cvt_pk_bf16_f32 v0, v0, v177
	ds_write_b16 v109, v0 offset:64
	v_mul_f32_e32 v0, v120, v17
	v_cvt_pk_bf16_f32 v0, v0, v177
	ds_write_b16 v109, v0 offset:128
	v_mul_f32_e32 v0, v120, v1
	v_cvt_pk_bf16_f32 v0, v0, v177
	ds_write_b16 v109, v0 offset:192
	v_mul_f32_e32 v0, v119, v18
	v_cvt_pk_bf16_f32 v0, v0, v177
	ds_write_b16 v109, v0 offset:256
	v_mul_f32_e32 v0, v119, v2
	v_cvt_pk_bf16_f32 v0, v0, v177
	ds_write_b16 v109, v0 offset:320
	v_mul_f32_e32 v0, v118, v19
	v_cvt_pk_bf16_f32 v0, v0, v177
	ds_write_b16 v109, v0 offset:384
	v_mul_f32_e32 v0, v118, v3
	v_cvt_pk_bf16_f32 v0, v0, v177
	ds_write_b16 v109, v0 offset:448
	v_mul_f32_e32 v0, v117, v20
	v_cvt_pk_bf16_f32 v0, v0, v177
	ds_write_b16 v109, v0 offset:1024
	v_mul_f32_e32 v0, v117, v4
	v_cvt_pk_bf16_f32 v0, v0, v177
	ds_write_b16 v109, v0 offset:1088
	v_mul_f32_e32 v0, v116, v21
	v_cvt_pk_bf16_f32 v0, v0, v177
	ds_write_b16 v109, v0 offset:1152
	v_mul_f32_e32 v0, v116, v5
	v_cvt_pk_bf16_f32 v0, v0, v177
	ds_write_b16 v109, v0 offset:1216
	v_mul_f32_e32 v0, v115, v22
	v_cvt_pk_bf16_f32 v0, v0, v177
	ds_write_b16 v109, v0 offset:1280
	v_mul_f32_e32 v0, v115, v6
	v_cvt_pk_bf16_f32 v0, v0, v177
	ds_write_b16 v109, v0 offset:1344
	v_mul_f32_e32 v0, v113, v23
	v_cvt_pk_bf16_f32 v0, v0, v177
	ds_write_b16 v109, v0 offset:1408
	v_mul_f32_e32 v0, v113, v7
	v_cvt_pk_bf16_f32 v0, v0, v177
	ds_write_b16 v109, v0 offset:1472
	v_mul_f32_e32 v0, v114, v24
	v_cvt_pk_bf16_f32 v0, v0, v177
	ds_write_b16 v109, v0 offset:2048
	v_mul_f32_e32 v0, v114, v8
	v_cvt_pk_bf16_f32 v0, v0, v177
	ds_write_b16 v109, v0 offset:2112
	v_mul_f32_e32 v0, v112, v25
	v_cvt_pk_bf16_f32 v0, v0, v177
	ds_write_b16 v109, v0 offset:2176
	v_mul_f32_e32 v0, v112, v9
	v_cvt_pk_bf16_f32 v0, v0, v177
	ds_write_b16 v109, v0 offset:2240
	v_mul_f32_e32 v0, v111, v26
	v_cvt_pk_bf16_f32 v0, v0, v177
	ds_write_b16 v109, v0 offset:2304
	v_mul_f32_e32 v0, v111, v10
	v_cvt_pk_bf16_f32 v0, v0, v177
	ds_write_b16 v109, v0 offset:2368
	v_mul_f32_e32 v0, v110, v27
	v_cvt_pk_bf16_f32 v0, v0, v177
	ds_write_b16 v109, v0 offset:2432
	v_mul_f32_e32 v0, v110, v11
	v_cvt_pk_bf16_f32 v0, v0, v177
	ds_write_b16 v109, v0 offset:2496
	v_mul_f32_e32 v0, v108, v28
	v_cvt_pk_bf16_f32 v0, v0, v177
	ds_write_b16 v109, v0 offset:3072
	v_mul_f32_e32 v0, v108, v12
	v_cvt_pk_bf16_f32 v0, v0, v177
	ds_write_b16 v109, v0 offset:3136
	v_mul_f32_e32 v0, v107, v29
	v_cvt_pk_bf16_f32 v0, v0, v177
	ds_write_b16 v109, v0 offset:3200
	v_mul_f32_e32 v0, v107, v13
	v_cvt_pk_bf16_f32 v0, v0, v177
	ds_write_b16 v109, v0 offset:3264
	v_mul_f32_e32 v0, v106, v30
	v_cvt_pk_bf16_f32 v0, v0, v177
	ds_write_b16 v109, v0 offset:3328
	v_mul_f32_e32 v0, v106, v14
	v_cvt_pk_bf16_f32 v0, v0, v177
	ds_write_b16 v109, v0 offset:3392
	v_mul_f32_e32 v0, v105, v31
	v_cvt_pk_bf16_f32 v0, v0, v177
	ds_write_b16 v109, v0 offset:3456
	v_mul_f32_e32 v0, v105, v15
	v_cvt_pk_bf16_f32 v0, v0, v177
	ds_write_b16 v109, v0 offset:3520
	s_waitcnt lgkmcnt(0)
	ds_read_b128 v[0:3], v122
	ds_read_b128 v[4:7], v123
	ds_read_b128 v[8:11], v124
	ds_read_b128 v[12:15], v125
	s_waitcnt lgkmcnt(3)
	global_store_dwordx4 v[96:97], v[0:3], off offset:128
	s_waitcnt lgkmcnt(2)
	global_store_dwordx4 v[98:99], v[4:7], off offset:128
	s_waitcnt lgkmcnt(1)
	global_store_dwordx4 v[100:101], v[8:11], off offset:128
	s_waitcnt lgkmcnt(0)
	global_store_dwordx4 v[102:103], v[12:15], off offset:128
	s_waitcnt lgkmcnt(0)
	s_waitcnt vmcnt(7)
	ds_write_b128 v146, v[226:229]
	s_waitcnt vmcnt(6)
	ds_write_b128 v146, v[230:233] offset:8192
	s_waitcnt vmcnt(5)
	ds_write_b128 v146, v[234:237] offset:16384
	s_waitcnt vmcnt(4)
	ds_write_b128 v146, v[238:241] offset:24576
	s_waitcnt lgkmcnt(0)
	s_barrier
	global_load_dwordx4 v[226:229], v[142:143], off
	global_load_dwordx4 v[230:233], v[142:143], off offset:128
	global_load_dwordx4 v[234:237], v[142:143], off offset:256
	global_load_dwordx4 v[238:241], v[142:143], off offset:384
	ds_read_b128 v[0:3], v104
	ds_read_b128 v[4:7], v104 offset:512
	s_waitcnt lgkmcnt(1)
	v_mfma_f32_32x32x16_bf16 v[16:31], v[92:95], v[0:3], 0
	ds_read_b128 v[126:129], v104 offset:2048
	ds_read_b128 v[130:133], v104 offset:2560
	s_waitcnt lgkmcnt(2)
	v_mfma_f32_32x32x16_bf16 v[0:15], v[92:95], v[4:7], 0
	s_waitcnt lgkmcnt(1)
	v_mfma_f32_32x32x16_bf16 v[16:31], v[88:91], v[126:129], v[16:31]
	s_waitcnt lgkmcnt(0)
	v_mfma_f32_32x32x16_bf16 v[0:15], v[88:91], v[130:133], v[0:15]
	ds_read_b128 v[126:129], v104 offset:4096
	ds_read_b128 v[130:133], v104 offset:4608
	s_waitcnt lgkmcnt(1)
	v_mfma_f32_32x32x16_bf16 v[16:31], v[84:87], v[126:129], v[16:31]
	s_waitcnt lgkmcnt(0)
	v_mfma_f32_32x32x16_bf16 v[0:15], v[84:87], v[130:133], v[0:15]
	ds_read_b128 v[126:129], v104 offset:6144
	ds_read_b128 v[130:133], v104 offset:6656
	s_waitcnt lgkmcnt(1)
	v_mfma_f32_32x32x16_bf16 v[16:31], v[80:83], v[126:129], v[16:31]
	s_waitcnt lgkmcnt(0)
	v_mfma_f32_32x32x16_bf16 v[0:15], v[80:83], v[130:133], v[0:15]
	ds_read_b128 v[126:129], v104 offset:8192
	ds_read_b128 v[130:133], v104 offset:8704
	s_waitcnt lgkmcnt(1)
	v_mfma_f32_32x32x16_bf16 v[16:31], v[76:79], v[126:129], v[16:31]
	s_waitcnt lgkmcnt(0)
	v_mfma_f32_32x32x16_bf16 v[0:15], v[76:79], v[130:133], v[0:15]
	ds_read_b128 v[126:129], v104 offset:10240
	ds_read_b128 v[130:133], v104 offset:10752
	s_waitcnt lgkmcnt(1)
	v_mfma_f32_32x32x16_bf16 v[16:31], v[72:75], v[126:129], v[16:31]
	s_waitcnt lgkmcnt(0)
; __device__ __forceinline__ int crow(int r,int hi){return (r&3)+8*(r>>2)+4*hi;}
; #define XLAS __attribute__((address_space(3)))
; __device__ __forceinline__ int crow(int r, int hi) { return (r & 3) + 8 * (r >> 2) + 4 * hi; }
; __device__ __forceinline__ unsigned pk(float lo, float hi) { return pg8::cvt_pk_bf16(lo, hi); }
; #define X_STOREV(buf) do { _Pragma("unroll") for (int i_ = 0; i_ < 4; ++i_) *(XLAS u32x4*)(lds + (buf) + (wid + 8 * i_) * 1024 + lane * 16) = st[i_]; } while (0)
; __device__ __forceinline__ void unit(int b, int h, int qblk, const bf16_t* __restrict__ CQ, const bf16_t* __restrict__ CK, const bf16_t* __restrict__ CVT, bf16_t* __restrict__ CO, XLAS unsigned char* lds, const int wv) {
;     ...
;         for (int j = 0; j < 16; ++j)
; #pragma unroll
;             for (int dt = 0; dt < 2; ++dt) {
;                 const bf16x8 vf = *(const XLAS bf16x8*)(lds + buf + voff + dt * 512 + j * 2048);
;                 o[dt] = __builtin_amdgcn_mfma_f32_32x32x16_bf16(__builtin_bit_cast(bf16x8, pw[j]), vf, o[dt], 0, 0, 0);
;             }
; #pragma unroll
;         for (int r = 0; r < 16; ++r) { const int orow = crow(r, hi);
; #pragma unroll
;             for (int dt = 0; dt < 2; ++dt) { const unsigned w = pk(o[dt][r] * rli[r], 0.f); stg[orow * 64 + dt * 32 + r32] = (bf16_t)(w & 0xffffu); } }
;         asm volatile("s_waitcnt lgkmcnt(0)" ::: "memory");
; #pragma unroll
;         for (int i = 0; i < 4; ++i) { const int row = i * 8 + (lane >> 3), ch = lane & 7; const u32x4 v = *(const XLAS u32x4*)(stg + row * 64 + ch * 8); *(u32x4*)(Ow + (size_t)row * 1024 + c * 64 + ch * 8) = v; }
;         asm volatile("s_waitcnt lgkmcnt(0)" ::: "memory");
;         if (c < 3) X_STOREV(nbuf);
;         __syncthreads();
	v_mfma_f32_32x32x16_bf16 v[0:15], v[72:75], v[130:133], v[0:15]
	ds_read_b128 v[126:129], v104 offset:12288
	ds_read_b128 v[130:133], v104 offset:12800
	s_waitcnt lgkmcnt(1)
	v_mfma_f32_32x32x16_bf16 v[16:31], v[68:71], v[126:129], v[16:31]
	s_waitcnt lgkmcnt(0)
	v_mfma_f32_32x32x16_bf16 v[0:15], v[68:71], v[130:133], v[0:15]
	ds_read_b128 v[126:129], v104 offset:14336
	ds_read_b128 v[130:133], v104 offset:14848
	s_waitcnt lgkmcnt(1)
	v_mfma_f32_32x32x16_bf16 v[16:31], v[64:67], v[126:129], v[16:31]
	s_waitcnt lgkmcnt(0)
	v_mfma_f32_32x32x16_bf16 v[0:15], v[64:67], v[130:133], v[0:15]
	ds_read_b128 v[126:129], v104 offset:16384
	ds_read_b128 v[130:133], v104 offset:16896
	s_waitcnt lgkmcnt(1)
	v_mfma_f32_32x32x16_bf16 v[16:31], v[60:63], v[126:129], v[16:31]
	s_waitcnt lgkmcnt(0)
	v_mfma_f32_32x32x16_bf16 v[0:15], v[60:63], v[130:133], v[0:15]
	ds_read_b128 v[126:129], v104 offset:18432
	ds_read_b128 v[130:133], v104 offset:18944
	s_waitcnt lgkmcnt(1)
	v_mfma_f32_32x32x16_bf16 v[16:31], v[56:59], v[126:129], v[16:31]
	s_waitcnt lgkmcnt(0)
	v_mfma_f32_32x32x16_bf16 v[0:15], v[56:59], v[130:133], v[0:15]
	ds_read_b128 v[126:129], v104 offset:20480
	ds_read_b128 v[130:133], v104 offset:20992
	s_waitcnt lgkmcnt(1)
	v_mfma_f32_32x32x16_bf16 v[16:31], v[52:55], v[126:129], v[16:31]
	s_waitcnt lgkmcnt(0)
	v_mfma_f32_32x32x16_bf16 v[0:15], v[52:55], v[130:133], v[0:15]
	ds_read_b128 v[126:129], v104 offset:22528
	ds_read_b128 v[130:133], v104 offset:23040
	s_waitcnt lgkmcnt(1)
	v_mfma_f32_32x32x16_bf16 v[16:31], v[48:51], v[126:129], v[16:31]
	s_waitcnt lgkmcnt(0)
	v_mfma_f32_32x32x16_bf16 v[0:15], v[48:51], v[130:133], v[0:15]
	ds_read_b128 v[126:129], v104 offset:24576
	ds_read_b128 v[130:133], v104 offset:25088
	s_waitcnt lgkmcnt(1)
	v_mfma_f32_32x32x16_bf16 v[16:31], v[44:47], v[126:129], v[16:31]
	s_waitcnt lgkmcnt(0)
	v_mfma_f32_32x32x16_bf16 v[0:15], v[44:47], v[130:133], v[0:15]
	ds_read_b128 v[126:129], v104 offset:26624
	ds_read_b128 v[130:133], v104 offset:27136
	s_waitcnt lgkmcnt(1)
	v_mfma_f32_32x32x16_bf16 v[16:31], v[40:43], v[126:129], v[16:31]
	s_waitcnt lgkmcnt(0)
	v_mfma_f32_32x32x16_bf16 v[0:15], v[40:43], v[130:133], v[0:15]
	ds_read_b128 v[126:129], v104 offset:28672
	ds_read_b128 v[130:133], v104 offset:29184
	s_waitcnt lgkmcnt(1)
	v_mfma_f32_32x32x16_bf16 v[16:31], v[36:39], v[126:129], v[16:31]
	ds_read_b128 v[126:129], v104 offset:30720
	s_waitcnt lgkmcnt(1)
	v_mfma_f32_32x32x16_bf16 v[0:15], v[36:39], v[130:133], v[0:15]
	ds_read_b128 v[130:133], v104 offset:31232
	s_waitcnt lgkmcnt(1)
	v_mfma_f32_32x32x16_bf16 v[16:31], v[32:35], v[126:129], v[16:31]
	s_nop 0
	s_nop 6
	v_mul_f32_e32 v16, v121, v16
	s_waitcnt lgkmcnt(0)
	v_mfma_f32_32x32x16_bf16 v[0:15], v[32:35], v[130:133], v[0:15]
	v_cvt_pk_bf16_f32 v16, v16, v177
	ds_write_b16 v109, v16
	s_nop 10
	v_mul_f32_e32 v0, v121, v0
	v_cvt_pk_bf16_f32 v0, v0, v177
	ds_write_b16 v109, v0 offset:64
	v_mul_f32_e32 v0, v120, v17
	v_cvt_pk_bf16_f32 v0, v0, v177
	ds_write_b16 v109, v0 offset:128
	v_mul_f32_e32 v0, v120, v1
	v_cvt_pk_bf16_f32 v0, v0, v177
	ds_write_b16 v109, v0 offset:192
	v_mul_f32_e32 v0, v119, v18
	v_cvt_pk_bf16_f32 v0, v0, v177
	ds_write_b16 v109, v0 offset:256
	v_mul_f32_e32 v0, v119, v2
	v_cvt_pk_bf16_f32 v0, v0, v177
	ds_write_b16 v109, v0 offset:320
	v_mul_f32_e32 v0, v118, v19
	v_cvt_pk_bf16_f32 v0, v0, v177
	ds_write_b16 v109, v0 offset:384
	v_mul_f32_e32 v0, v118, v3
	v_cvt_pk_bf16_f32 v0, v0, v177
	ds_write_b16 v109, v0 offset:448
	v_mul_f32_e32 v0, v117, v20
	v_cvt_pk_bf16_f32 v0, v0, v177
	ds_write_b16 v109, v0 offset:1024
	v_mul_f32_e32 v0, v117, v4
	v_cvt_pk_bf16_f32 v0, v0, v177
	ds_write_b16 v109, v0 offset:1088
	v_mul_f32_e32 v0, v116, v21
	v_cvt_pk_bf16_f32 v0, v0, v177
	ds_write_b16 v109, v0 offset:1152
	v_mul_f32_e32 v0, v116, v5
	v_cvt_pk_bf16_f32 v0, v0, v177
	ds_write_b16 v109, v0 offset:1216
	v_mul_f32_e32 v0, v115, v22
	v_cvt_pk_bf16_f32 v0, v0, v177
	ds_write_b16 v109, v0 offset:1280
	v_mul_f32_e32 v0, v115, v6
	v_cvt_pk_bf16_f32 v0, v0, v177
	ds_write_b16 v109, v0 offset:1344
	v_mul_f32_e32 v0, v113, v23
	v_cvt_pk_bf16_f32 v0, v0, v177
	ds_write_b16 v109, v0 offset:1408
	v_mul_f32_e32 v0, v113, v7
	v_cvt_pk_bf16_f32 v0, v0, v177
	ds_write_b16 v109, v0 offset:1472
	v_mul_f32_e32 v0, v114, v24
	v_cvt_pk_bf16_f32 v0, v0, v177
	ds_write_b16 v109, v0 offset:2048
	v_mul_f32_e32 v0, v114, v8
	v_cvt_pk_bf16_f32 v0, v0, v177
	ds_write_b16 v109, v0 offset:2112
	v_mul_f32_e32 v0, v112, v25
	v_cvt_pk_bf16_f32 v0, v0, v177
	ds_write_b16 v109, v0 offset:2176
	v_mul_f32_e32 v0, v112, v9
	v_cvt_pk_bf16_f32 v0, v0, v177
	ds_write_b16 v109, v0 offset:2240
	v_mul_f32_e32 v0, v111, v26
	v_cvt_pk_bf16_f32 v0, v0, v177
	ds_write_b16 v109, v0 offset:2304
	v_mul_f32_e32 v0, v111, v10
	v_cvt_pk_bf16_f32 v0, v0, v177
	ds_write_b16 v109, v0 offset:2368
	v_mul_f32_e32 v0, v110, v27
	v_cvt_pk_bf16_f32 v0, v0, v177
	ds_write_b16 v109, v0 offset:2432
	v_mul_f32_e32 v0, v110, v11
	v_cvt_pk_bf16_f32 v0, v0, v177
	ds_write_b16 v109, v0 offset:2496
	v_mul_f32_e32 v0, v108, v28
	v_cvt_pk_bf16_f32 v0, v0, v177
	ds_write_b16 v109, v0 offset:3072
	v_mul_f32_e32 v0, v108, v12
	v_cvt_pk_bf16_f32 v0, v0, v177
	ds_write_b16 v109, v0 offset:3136
	v_mul_f32_e32 v0, v107, v29
	v_cvt_pk_bf16_f32 v0, v0, v177
	ds_write_b16 v109, v0 offset:3200
	v_mul_f32_e32 v0, v107, v13
	v_cvt_pk_bf16_f32 v0, v0, v177
	ds_write_b16 v109, v0 offset:3264
	v_mul_f32_e32 v0, v106, v30
	v_cvt_pk_bf16_f32 v0, v0, v177
	ds_write_b16 v109, v0 offset:3328
	v_mul_f32_e32 v0, v106, v14
	v_cvt_pk_bf16_f32 v0, v0, v177
	ds_write_b16 v109, v0 offset:3392
	v_mul_f32_e32 v0, v105, v31
	v_cvt_pk_bf16_f32 v0, v0, v177
	ds_write_b16 v109, v0 offset:3456
	v_mul_f32_e32 v0, v105, v15
	v_cvt_pk_bf16_f32 v0, v0, v177
	ds_write_b16 v109, v0 offset:3520
	s_waitcnt lgkmcnt(0)
	ds_read_b128 v[0:3], v122
	ds_read_b128 v[4:7], v123
	ds_read_b128 v[8:11], v124
	ds_read_b128 v[12:15], v125
	s_waitcnt lgkmcnt(3)
	global_store_dwordx4 v[96:97], v[0:3], off offset:256
	s_waitcnt lgkmcnt(2)
	global_store_dwordx4 v[98:99], v[4:7], off offset:256
	s_waitcnt lgkmcnt(1)
	global_store_dwordx4 v[100:101], v[8:11], off offset:256
	s_waitcnt lgkmcnt(0)
	global_store_dwordx4 v[102:103], v[12:15], off offset:256
	s_waitcnt lgkmcnt(0)
	s_waitcnt vmcnt(7)
	ds_write_b128 v146, v[226:229] offset:32768
	s_waitcnt vmcnt(6)
	ds_write_b128 v146, v[230:233] offset:40960
	s_waitcnt vmcnt(5)
	ds_write_b128 v146, v[234:237] offset:49152
	s_waitcnt vmcnt(4)
	ds_write_b128 v146, v[238:241] offset:57344
	s_waitcnt lgkmcnt(0)
	s_barrier
; __device__ __forceinline__ int crow(int r,int hi){return (r&3)+8*(r>>2)+4*hi;}
; #define XLAS __attribute__((address_space(3)))
; __device__ __forceinline__ int crow(int r, int hi) { return (r & 3) + 8 * (r >> 2) + 4 * hi; }
; __device__ __forceinline__ unsigned pk(float lo, float hi) { return pg8::cvt_pk_bf16(lo, hi); }
; __device__ __forceinline__ void unit(int b, int h, int qblk, const bf16_t* __restrict__ CQ, const bf16_t* __restrict__ CK, const bf16_t* __restrict__ CVT, bf16_t* __restrict__ CO, XLAS unsigned char* lds, const int wv) {
;     ...
;         for (int j = 0; j < 16; ++j)
; #pragma unroll
;             for (int dt = 0; dt < 2; ++dt) {
;                 const bf16x8 vf = *(const XLAS bf16x8*)(lds + buf + voff + dt * 512 + j * 2048);
;                 o[dt] = __builtin_amdgcn_mfma_f32_32x32x16_bf16(__builtin_bit_cast(bf16x8, pw[j]), vf, o[dt], 0, 0, 0);
;             }
; #pragma unroll
;         for (int r = 0; r < 16; ++r) { const int orow = crow(r, hi);
; #pragma unroll
;             for (int dt = 0; dt < 2; ++dt) { const unsigned w = pk(o[dt][r] * rli[r], 0.f); stg[orow * 64 + dt * 32 + r32] = (bf16_t)(w & 0xffffu); } }
	ds_read_b128 v[0:3], v104 offset:32768
	ds_read_b128 v[4:7], v104 offset:33280
	s_waitcnt lgkmcnt(1)
	v_mfma_f32_32x32x16_bf16 v[16:31], v[92:95], v[0:3], 0
	s_waitcnt lgkmcnt(0)
	v_mfma_f32_32x32x16_bf16 v[0:15], v[92:95], v[4:7], 0
	ds_read_b128 v[92:95], v104 offset:34816
	ds_read_b128 v[126:129], v104 offset:35328
	s_waitcnt lgkmcnt(1)
	v_mfma_f32_32x32x16_bf16 v[16:31], v[88:91], v[92:95], v[16:31]
	s_waitcnt lgkmcnt(0)
	v_mfma_f32_32x32x16_bf16 v[0:15], v[88:91], v[126:129], v[0:15]
	ds_read_b128 v[88:91], v104 offset:36864
	ds_read_b128 v[92:95], v104 offset:37376
	s_waitcnt lgkmcnt(1)
	v_mfma_f32_32x32x16_bf16 v[16:31], v[84:87], v[88:91], v[16:31]
	s_waitcnt lgkmcnt(0)
	v_mfma_f32_32x32x16_bf16 v[0:15], v[84:87], v[92:95], v[0:15]
	ds_read_b128 v[84:87], v104 offset:38912
	ds_read_b128 v[88:91], v104 offset:39424
	s_waitcnt lgkmcnt(1)
	v_mfma_f32_32x32x16_bf16 v[16:31], v[80:83], v[84:87], v[16:31]
	s_waitcnt lgkmcnt(0)
	v_mfma_f32_32x32x16_bf16 v[0:15], v[80:83], v[88:91], v[0:15]
	ds_read_b128 v[80:83], v104 offset:40960
	ds_read_b128 v[84:87], v104 offset:41472
	s_waitcnt lgkmcnt(1)
	v_mfma_f32_32x32x16_bf16 v[16:31], v[76:79], v[80:83], v[16:31]
	s_waitcnt lgkmcnt(0)
	v_mfma_f32_32x32x16_bf16 v[0:15], v[76:79], v[84:87], v[0:15]
	ds_read_b128 v[76:79], v104 offset:43008
	ds_read_b128 v[80:83], v104 offset:43520
	s_waitcnt lgkmcnt(1)
	v_mfma_f32_32x32x16_bf16 v[16:31], v[72:75], v[76:79], v[16:31]
	s_waitcnt lgkmcnt(0)
	v_mfma_f32_32x32x16_bf16 v[0:15], v[72:75], v[80:83], v[0:15]
	ds_read_b128 v[72:75], v104 offset:45056
	ds_read_b128 v[76:79], v104 offset:45568
	s_waitcnt lgkmcnt(1)
	v_mfma_f32_32x32x16_bf16 v[16:31], v[68:71], v[72:75], v[16:31]
	s_waitcnt lgkmcnt(0)
	v_mfma_f32_32x32x16_bf16 v[0:15], v[68:71], v[76:79], v[0:15]
	ds_read_b128 v[68:71], v104 offset:47104
	ds_read_b128 v[72:75], v104 offset:47616
	s_waitcnt lgkmcnt(1)
	v_mfma_f32_32x32x16_bf16 v[16:31], v[64:67], v[68:71], v[16:31]
	s_waitcnt lgkmcnt(0)
	v_mfma_f32_32x32x16_bf16 v[0:15], v[64:67], v[72:75], v[0:15]
	ds_read_b128 v[64:67], v104 offset:49152
	ds_read_b128 v[68:71], v104 offset:49664
	s_waitcnt lgkmcnt(1)
	v_mfma_f32_32x32x16_bf16 v[16:31], v[60:63], v[64:67], v[16:31]
	s_waitcnt lgkmcnt(0)
	v_mfma_f32_32x32x16_bf16 v[0:15], v[60:63], v[68:71], v[0:15]
	ds_read_b128 v[60:63], v104 offset:51200
	ds_read_b128 v[64:67], v104 offset:51712
	s_waitcnt lgkmcnt(1)
	v_mfma_f32_32x32x16_bf16 v[16:31], v[56:59], v[60:63], v[16:31]
	s_waitcnt lgkmcnt(0)
	v_mfma_f32_32x32x16_bf16 v[0:15], v[56:59], v[64:67], v[0:15]
	ds_read_b128 v[56:59], v104 offset:53248
	ds_read_b128 v[60:63], v104 offset:53760
	s_waitcnt lgkmcnt(1)
	v_mfma_f32_32x32x16_bf16 v[16:31], v[52:55], v[56:59], v[16:31]
	s_waitcnt lgkmcnt(0)
	v_mfma_f32_32x32x16_bf16 v[0:15], v[52:55], v[60:63], v[0:15]
	ds_read_b128 v[52:55], v104 offset:55296
	ds_read_b128 v[56:59], v104 offset:55808
	s_waitcnt lgkmcnt(1)
	v_mfma_f32_32x32x16_bf16 v[16:31], v[48:51], v[52:55], v[16:31]
	s_waitcnt lgkmcnt(0)
	v_mfma_f32_32x32x16_bf16 v[0:15], v[48:51], v[56:59], v[0:15]
	ds_read_b128 v[48:51], v104 offset:57344
	ds_read_b128 v[52:55], v104 offset:57856
	s_waitcnt lgkmcnt(1)
	v_mfma_f32_32x32x16_bf16 v[16:31], v[44:47], v[48:51], v[16:31]
	s_waitcnt lgkmcnt(0)
	v_mfma_f32_32x32x16_bf16 v[0:15], v[44:47], v[52:55], v[0:15]
	ds_read_b128 v[44:47], v104 offset:59392
	ds_read_b128 v[48:51], v104 offset:59904
	s_waitcnt lgkmcnt(1)
	v_mfma_f32_32x32x16_bf16 v[16:31], v[40:43], v[44:47], v[16:31]
	s_waitcnt lgkmcnt(0)
	v_mfma_f32_32x32x16_bf16 v[0:15], v[40:43], v[48:51], v[0:15]
	ds_read_b128 v[40:43], v104 offset:61440
	ds_read_b128 v[44:47], v104 offset:61952
	s_waitcnt lgkmcnt(1)
	v_mfma_f32_32x32x16_bf16 v[16:31], v[36:39], v[40:43], v[16:31]
	s_waitcnt lgkmcnt(0)
	v_mfma_f32_32x32x16_bf16 v[0:15], v[36:39], v[44:47], v[0:15]
	ds_read_b128 v[36:39], v104 offset:63488
	ds_read_b128 v[40:43], v104 offset:64000
	s_waitcnt lgkmcnt(1)
	v_mfma_f32_32x32x16_bf16 v[16:31], v[32:35], v[36:39], v[16:31]
	s_waitcnt lgkmcnt(0)
	v_mfma_f32_32x32x16_bf16 v[0:15], v[32:35], v[40:43], v[0:15]
	s_nop 9
	v_mul_f32_e32 v16, v121, v16
	v_cvt_pk_bf16_f32 v16, v16, v177
	ds_write_b16 v109, v16
	v_mul_f32_e32 v0, v121, v0
	v_cvt_pk_bf16_f32 v0, v0, v177
	ds_write_b16 v109, v0 offset:64
	v_mul_f32_e32 v0, v120, v17
	v_cvt_pk_bf16_f32 v0, v0, v177
	ds_write_b16 v109, v0 offset:128
	v_mul_f32_e32 v0, v120, v1
	v_cvt_pk_bf16_f32 v0, v0, v177
	ds_write_b16 v109, v0 offset:192
	v_mul_f32_e32 v0, v119, v18
	v_cvt_pk_bf16_f32 v0, v0, v177
	ds_write_b16 v109, v0 offset:256
	v_mul_f32_e32 v0, v119, v2
	v_cvt_pk_bf16_f32 v0, v0, v177
	ds_write_b16 v109, v0 offset:320
	v_mul_f32_e32 v0, v118, v19
	v_cvt_pk_bf16_f32 v0, v0, v177
	ds_write_b16 v109, v0 offset:384
	v_mul_f32_e32 v0, v118, v3
	v_cvt_pk_bf16_f32 v0, v0, v177
	ds_write_b16 v109, v0 offset:448
	v_mul_f32_e32 v0, v117, v20
	v_cvt_pk_bf16_f32 v0, v0, v177
	ds_write_b16 v109, v0 offset:1024
	v_mul_f32_e32 v0, v117, v4
	v_cvt_pk_bf16_f32 v0, v0, v177
	ds_write_b16 v109, v0 offset:1088
	v_mul_f32_e32 v0, v116, v21
	v_cvt_pk_bf16_f32 v0, v0, v177
	ds_write_b16 v109, v0 offset:1152
	v_mul_f32_e32 v0, v116, v5
	v_cvt_pk_bf16_f32 v0, v0, v177
	ds_write_b16 v109, v0 offset:1216
	v_mul_f32_e32 v0, v115, v22
	v_cvt_pk_bf16_f32 v0, v0, v177
	ds_write_b16 v109, v0 offset:1280
	v_mul_f32_e32 v0, v115, v6
	v_cvt_pk_bf16_f32 v0, v0, v177
	ds_write_b16 v109, v0 offset:1344
	v_mul_f32_e32 v0, v113, v23
	v_cvt_pk_bf16_f32 v0, v0, v177
	ds_write_b16 v109, v0 offset:1408
	v_mul_f32_e32 v0, v113, v7
	v_cvt_pk_bf16_f32 v0, v0, v177
	ds_write_b16 v109, v0 offset:1472
	v_mul_f32_e32 v0, v114, v24
; __device__ __forceinline__ int mk_lane() { int l = (int)__builtin_amdgcn_mbcnt_hi(~0u, __builtin_amdgcn_mbcnt_lo(~0u, 0u)); asm volatile("" : "+v"(l)); return l; }
; __device__ __forceinline__ int crow(int r,int hi){return (r&3)+8*(r>>2)+4*hi;}
; #define XLAS __attribute__((address_space(3)))
; __device__ __forceinline__ int crow(int r, int hi) { return (r & 3) + 8 * (r >> 2) + 4 * hi; }
; __device__ __forceinline__ unsigned pk(float lo, float hi) { return pg8::cvt_pk_bf16(lo, hi); }
; __device__ __forceinline__ void unit(int b, int h, int qblk, const bf16_t* __restrict__ CQ, const bf16_t* __restrict__ CK, const bf16_t* __restrict__ CVT, bf16_t* __restrict__ CO, XLAS unsigned char* lds, const int wv) {
;     const int tid = wv * 64 + mk_lane(), lane = tid & 63, r32 = lane & 31, hi = lane >> 5; const int wid = __builtin_amdgcn_readfirstlane(tid >> 6);
;     const size_t qrow0 = (size_t)b * 4096 + (size_t)qblk * 256 + wid * 32;
;     const bf16_t* Qw = CQ + (qrow0 + r32) * 1024 + h * 256 + hi * 8;
;     const bf16_t* Kg = CK + ((size_t)b * 256 + lane) * 1024 + h * 256 + wid * 8;
;     const bf16_t* Vg = CVT + ((size_t)h * 256 + lane) * 2048 + (size_t)b * 256 + wid * 8;
;     u32x4 st[4];
;     ...
;     const int kswz = (r32 & ~12) | ((r32 & 4) << 1) | ((r32 & 8) >> 1);
;     const int koff = hi * 4096 + kswz * 16;
;     const int voff = hi * 1024 + r32 * 16;
;     f32x16 s[8];
; #pragma unroll
;     for (int kt = 0; kt < 8; ++kt) s[kt] = f32x16{};
;     X_LOADK(0);
;     bf16x8 qfa[4][4];
; #pragma unroll
;     for (int dc = 0; dc < 4; ++dc)
; #pragma unroll
;         for (int ks = 0; ks < 4; ++ks) qfa[dc][ks] = *(const bf16x8*)(Qw + dc * 64 + ks * 16);
;     X_STOREK(XB0);
;     __syncthreads();
;     ...
;         for (int r = 0; r < 16; ++r) { const int orow = crow(r, hi);
; #pragma unroll
;             for (int dt = 0; dt < 2; ++dt) { const unsigned w = pk(o[dt][r] * rli[r], 0.f); stg[orow * 64 + dt * 32 + r32] = (bf16_t)(w & 0xffffu); } }
;         asm volatile("s_waitcnt lgkmcnt(0)" ::: "memory");
; #pragma unroll
;         for (int i = 0; i < 4; ++i) { const int row = i * 8 + (lane >> 3), ch = lane & 7; const u32x4 v = *(const XLAS u32x4*)(stg + row * 64 + ch * 8); *(u32x4*)(Ow + (size_t)row * 1024 + c * 64 + ch * 8) = v; }
;         asm volatile("s_waitcnt lgkmcnt(0)" ::: "memory");
;         if (c < 3) X_STOREV(nbuf);
;         __syncthreads();
	v_cvt_pk_bf16_f32 v0, v0, v177
	ds_write_b16 v109, v0 offset:2048
	v_mul_f32_e32 v0, v114, v8
	v_cvt_pk_bf16_f32 v0, v0, v177
	ds_write_b16 v109, v0 offset:2112
	v_mul_f32_e32 v0, v112, v25
	v_cvt_pk_bf16_f32 v0, v0, v177
	ds_write_b16 v109, v0 offset:2176
	v_mul_f32_e32 v0, v112, v9
	v_cvt_pk_bf16_f32 v0, v0, v177
	ds_write_b16 v109, v0 offset:2240
	v_mul_f32_e32 v0, v111, v26
	v_cvt_pk_bf16_f32 v0, v0, v177
	ds_write_b16 v109, v0 offset:2304
	v_mul_f32_e32 v0, v111, v10
	v_cvt_pk_bf16_f32 v0, v0, v177
	ds_write_b16 v109, v0 offset:2368
	v_mul_f32_e32 v0, v110, v27
	v_cvt_pk_bf16_f32 v0, v0, v177
	ds_write_b16 v109, v0 offset:2432
	v_mul_f32_e32 v0, v110, v11
	v_cvt_pk_bf16_f32 v0, v0, v177
	ds_write_b16 v109, v0 offset:2496
	v_mul_f32_e32 v0, v108, v28
	v_cvt_pk_bf16_f32 v0, v0, v177
	ds_write_b16 v109, v0 offset:3072
	v_mul_f32_e32 v0, v108, v12
	v_cvt_pk_bf16_f32 v0, v0, v177
	ds_write_b16 v109, v0 offset:3136
	v_mul_f32_e32 v0, v107, v29
	v_cvt_pk_bf16_f32 v0, v0, v177
	ds_write_b16 v109, v0 offset:3200
	v_mul_f32_e32 v0, v107, v13
	v_cvt_pk_bf16_f32 v0, v0, v177
	ds_write_b16 v109, v0 offset:3264
	v_mul_f32_e32 v0, v106, v30
	v_cvt_pk_bf16_f32 v0, v0, v177
	ds_write_b16 v109, v0 offset:3328
	v_mul_f32_e32 v0, v106, v14
	v_cvt_pk_bf16_f32 v0, v0, v177
	ds_write_b16 v109, v0 offset:3392
	v_mul_f32_e32 v0, v105, v31
	v_cvt_pk_bf16_f32 v0, v0, v177
	ds_write_b16 v109, v0 offset:3456
	v_mul_f32_e32 v0, v105, v15
	v_cvt_pk_bf16_f32 v0, v0, v177
	ds_write_b16 v109, v0 offset:3520
	s_waitcnt lgkmcnt(0)
	ds_read_b128 v[0:3], v122
	ds_read_b128 v[4:7], v123
	ds_read_b128 v[8:11], v124
	ds_read_b128 v[12:15], v125
	s_waitcnt lgkmcnt(3)
	global_store_dwordx4 v[96:97], v[0:3], off offset:384
	s_waitcnt lgkmcnt(2)
	global_store_dwordx4 v[98:99], v[4:7], off offset:384
	s_waitcnt lgkmcnt(1)
	global_store_dwordx4 v[100:101], v[8:11], off offset:384
	s_waitcnt lgkmcnt(0)
	global_store_dwordx4 v[102:103], v[12:15], off offset:384
	s_waitcnt lgkmcnt(0)
	s_barrier
	s_cbranch_scc0 .LBB0_1147
.LBB0_1145:
	v_mov_b32_e32 v189, v212
	s_ashr_i32 s14, s2, 6
	s_ashr_i32 s15, s14, 31
	v_add_u32_e32 v0, s20, v189
	s_lshl_b64 s[12:13], s[14:15], 12
	v_readfirstlane_b32 s27, v0
	s_ashr_i32 s29, s27, 6
	s_and_b32 s4, s21, 0xf00
	s_or_b32 s4, s12, s4
	s_lshl_b32 s12, s29, 5
	s_bfe_u32 s28, s2, 0x20004
	s_ashr_i32 s16, s12, 31
	s_add_u32 s12, s4, s12
	v_and_b32_e32 v190, 63, v189
	s_addc_u32 s13, s13, s16
	s_lshl_b64 s[16:17], s[14:15], 19
	v_lshl_or_b32 v0, v190, 11, s16
	v_mov_b32_e32 v1, s17
	s_lshl_b32 s16, s29, 3
	v_lshl_add_u64 v[0:1], s[8:9], 0, v[0:1]
	s_ashr_i32 s17, s16, 31
	s_lshl_b32 s4, s28, 9
	v_lshl_add_u64 v[0:1], v[0:1], 0, s[4:5]
	s_lshl_b64 s[16:17], s[16:17], 1
	v_lshl_add_u64 v[180:181], v[0:1], 0, s[16:17]
	v_add_co_u32_e32 v182, vcc, s22, v180
	v_and_b32_e32 v191, 31, v189
	s_nop 0
	v_addc_co_u32_e32 v183, vcc, 0, v181, vcc
	v_add_co_u32_e32 v184, vcc, s23, v180
	global_load_dwordx4 v[0:3], v[180:181], off
	global_load_dwordx4 v[4:7], v[182:183], off
	v_addc_co_u32_e32 v185, vcc, 0, v181, vcc
	v_add_co_u32_e32 v186, vcc, s24, v180
	v_or_b32_e32 v16, s12, v191
	s_nop 0
	v_addc_co_u32_e32 v187, vcc, 0, v181, vcc
	global_load_dwordx4 v[8:11], v[184:185], off
	global_load_dwordx4 v[12:15], v[186:187], off
	v_mov_b32_e32 v17, s13
	v_lshlrev_b64 v[16:17], 11, v[16:17]
	s_lshl_b32 s30, s28, 20
	v_bfe_u32 v192, v189, 5, 1
	v_lshl_or_b32 v176, v190, 12, s30
	v_lshl_add_u64 v[16:17], s[6:7], 0, v[16:17]
	v_lshl_add_u64 v[178:179], s[10:11], 0, v[176:177]
	v_lshl_add_u64 v[16:17], v[16:17], 0, s[4:5]
	v_lshlrev_b32_e32 v176, 4, v192
	v_lshl_add_u64 v[16:17], v[16:17], 0, v[176:177]
	global_load_dwordx4 v[194:197], v[16:17], off
	global_load_dwordx4 v[198:201], v[16:17], off offset:32
	global_load_dwordx4 v[202:205], v[16:17], off offset:64
	global_load_dwordx4 v[206:209], v[16:17], off offset:96
	global_load_dwordx4 v[172:175], v[16:17], off offset:128
	global_load_dwordx4 v[168:171], v[16:17], off offset:160
	global_load_dwordx4 v[164:167], v[16:17], off offset:192
	global_load_dwordx4 v[160:163], v[16:17], off offset:224
	global_load_dwordx4 v[156:159], v[16:17], off offset:256
	global_load_dwordx4 v[152:155], v[16:17], off offset:288
	global_load_dwordx4 v[148:151], v[16:17], off offset:320
	global_load_dwordx4 v[144:147], v[16:17], off offset:352
	global_load_dwordx4 v[140:143], v[16:17], off offset:384
	global_load_dwordx4 v[136:139], v[16:17], off offset:416
	global_load_dwordx4 v[132:135], v[16:17], off offset:448
	global_load_dwordx4 v[128:131], v[16:17], off offset:480
	v_lshlrev_b32_e32 v18, 1, v189
	v_lshrrev_b32_e32 v19, 1, v189
	v_and_b32_e32 v20, 19, v189
	v_and_b32_e32 v18, 8, v18
	v_and_b32_e32 v19, 4, v19
	v_or3_b32 v18, v20, v18, v19
	s_lshl_b32 s4, s29, 12
	v_lshlrev_b32_e32 v21, 12, v192
	v_lshlrev_b32_e32 v193, 4, v190
	v_lshlrev_b32_e32 v18, 4, v18
	s_add_i32 s4, s4, 0
	v_add3_u32 v176, 0, v21, v18
	v_add_u32_e32 v210, s4, v193
	s_lshl_b64 s[14:15], s[14:15], 9
	v_cmp_gt_u32_e32 vcc, 32, v190
	s_waitcnt vmcnt(0)
	ds_write_b128 v210, v[0:3]
	ds_write_b128 v210, v[4:7] offset:1024
	ds_write_b128 v210, v[8:11] offset:2048
	ds_write_b128 v210, v[12:15] offset:3072
	s_waitcnt lgkmcnt(0)
	s_barrier
; #define XLAS __attribute__((address_space(3)))
; #define X_LOADK(dc) do { _Pragma("unroll") for (int i_ = 0; i_ < 4; ++i_) st[i_] = *(const u32x4*)(Kg + (dc) * 64 + (size_t)i_ * 64 * 1024); } while (0)
; #define X_LOADV(c)  do { _Pragma("unroll") for (int i_ = 0; i_ < 4; ++i_) st[i_] = *(const u32x4*)(Vg + (size_t)(c) * 64 * 2048 + i_ * 64); } while (0)
; #define X_STOREK(buf) do { _Pragma("unroll") for (int i_ = 0; i_ < 4; ++i_) *(XLAS u32x4*)(lds + (buf) + wid * 4096 + (64 * i_ + lane) * 16) = st[i_]; } while (0)
; #define X_STOREV(buf) do { _Pragma("unroll") for (int i_ = 0; i_ < 4; ++i_) *(XLAS u32x4*)(lds + (buf) + (wid + 8 * i_) * 1024 + lane * 16) = st[i_]; } while (0)
; __device__ __forceinline__ void unit(int b, int h, int qblk, const bf16_t* __restrict__ CQ, const bf16_t* __restrict__ CK, const bf16_t* __restrict__ CVT, bf16_t* __restrict__ CO, XLAS unsigned char* lds, const int wv) {
;     ...
;     for (int dc = 0; dc < 4; ++dc) {
;         const int buf = (dc & 1) ? XB1 : XB0, nbuf = (dc & 1) ? XB0 : XB1;
;         if (dc < 3) X_LOADK(dc + 1); else X_LOADV(0);
; #pragma unroll
;         for (int kt = 0; kt < 8; ++kt)
; #pragma unroll
;             for (int ks = 0; ks < 4; ++ks) {
;                 const bf16x8 kf = *(const XLAS bf16x8*)(lds + buf + koff + kt * 512 + ks * 8192);
;                 s[kt] = __builtin_amdgcn_mfma_f32_32x32x16_bf16(kf, qfa[dc][ks], s[kt], 0, 0, 0);
;             }
;         if (dc < 3) X_STOREK(nbuf); else X_STOREV(nbuf);
;         __syncthreads();
	global_load_dwordx4 v[226:229], v[180:181], off offset:128
	global_load_dwordx4 v[230:233], v[182:183], off offset:128
	global_load_dwordx4 v[234:237], v[184:185], off offset:128
	global_load_dwordx4 v[238:241], v[186:187], off offset:128
	ds_read_b128 v[0:3], v176
	ds_read_b128 v[4:7], v176 offset:512
	s_waitcnt lgkmcnt(1)
	v_mfma_f32_32x32x16_bf16 v[112:127], v[0:3], v[194:197], 0
	s_waitcnt lgkmcnt(0)
	v_mfma_f32_32x32x16_bf16 v[96:111], v[4:7], v[194:197], 0
	ds_read_b128 v[0:3], v176 offset:1024
	ds_read_b128 v[4:7], v176 offset:1536
	s_waitcnt lgkmcnt(1)
	v_mfma_f32_32x32x16_bf16 v[80:95], v[0:3], v[194:197], 0
	s_waitcnt lgkmcnt(0)
	v_mfma_f32_32x32x16_bf16 v[64:79], v[4:7], v[194:197], 0
	ds_read_b128 v[0:3], v176 offset:8192
	ds_read_b128 v[4:7], v176 offset:8704
	s_waitcnt lgkmcnt(1)
	v_mfma_f32_32x32x16_bf16 v[112:127], v[0:3], v[198:201], v[112:127]
	s_waitcnt lgkmcnt(0)
	v_mfma_f32_32x32x16_bf16 v[96:111], v[4:7], v[198:201], v[96:111]
	ds_read_b128 v[0:3], v176 offset:9216
	ds_read_b128 v[4:7], v176 offset:9728
	s_waitcnt lgkmcnt(1)
	v_mfma_f32_32x32x16_bf16 v[80:95], v[0:3], v[198:201], v[80:95]
	s_waitcnt lgkmcnt(0)
	v_mfma_f32_32x32x16_bf16 v[64:79], v[4:7], v[198:201], v[64:79]
	ds_read_b128 v[0:3], v176 offset:16384
	ds_read_b128 v[4:7], v176 offset:16896
	s_waitcnt lgkmcnt(1)
	v_mfma_f32_32x32x16_bf16 v[112:127], v[0:3], v[202:205], v[112:127]
	s_waitcnt lgkmcnt(0)
	v_mfma_f32_32x32x16_bf16 v[96:111], v[4:7], v[202:205], v[96:111]
	ds_read_b128 v[0:3], v176 offset:17408
	ds_read_b128 v[4:7], v176 offset:17920
	s_waitcnt lgkmcnt(1)
	v_mfma_f32_32x32x16_bf16 v[80:95], v[0:3], v[202:205], v[80:95]
	s_waitcnt lgkmcnt(0)
	v_mfma_f32_32x32x16_bf16 v[64:79], v[4:7], v[202:205], v[64:79]
	ds_read_b128 v[0:3], v176 offset:24576
	ds_read_b128 v[4:7], v176 offset:25088
	s_waitcnt lgkmcnt(1)
	v_mfma_f32_32x32x16_bf16 v[112:127], v[0:3], v[206:209], v[112:127]
	s_waitcnt lgkmcnt(0)
	v_mfma_f32_32x32x16_bf16 v[96:111], v[4:7], v[206:209], v[96:111]
	ds_read_b128 v[0:3], v176 offset:25600
	ds_read_b128 v[4:7], v176 offset:26112
	s_waitcnt lgkmcnt(1)
	v_mfma_f32_32x32x16_bf16 v[80:95], v[0:3], v[206:209], v[80:95]
	s_waitcnt lgkmcnt(0)
	v_mfma_f32_32x32x16_bf16 v[64:79], v[4:7], v[206:209], v[64:79]
	ds_read_b128 v[0:3], v176 offset:2048
	ds_read_b128 v[4:7], v176 offset:2560
	s_waitcnt lgkmcnt(1)
	v_mfma_f32_32x32x16_bf16 v[48:63], v[0:3], v[194:197], 0
	ds_read_b128 v[0:3], v176 offset:10240
	ds_read_b128 v[8:11], v176 offset:10752
	s_waitcnt lgkmcnt(2)
	v_mfma_f32_32x32x16_bf16 v[32:47], v[4:7], v[194:197], 0
	s_waitcnt lgkmcnt(1)
	v_mfma_f32_32x32x16_bf16 v[48:63], v[0:3], v[198:201], v[48:63]
	ds_read_b128 v[0:3], v176 offset:18432
	ds_read_b128 v[12:15], v176 offset:18944
	s_waitcnt lgkmcnt(2)
	v_mfma_f32_32x32x16_bf16 v[32:47], v[8:11], v[198:201], v[32:47]
	s_waitcnt lgkmcnt(1)
	v_mfma_f32_32x32x16_bf16 v[48:63], v[0:3], v[202:205], v[48:63]
	ds_read_b128 v[0:3], v176 offset:26624
	ds_read_b128 v[16:19], v176 offset:27136
	s_waitcnt lgkmcnt(2)
	v_mfma_f32_32x32x16_bf16 v[32:47], v[12:15], v[202:205], v[32:47]
	s_waitcnt lgkmcnt(1)
	v_mfma_f32_32x32x16_bf16 v[48:63], v[0:3], v[206:209], v[48:63]
	ds_read_b128 v[0:3], v176 offset:3072
	ds_read_b128 v[4:7], v176 offset:3584
	s_waitcnt lgkmcnt(2)
	v_mfma_f32_32x32x16_bf16 v[32:47], v[16:19], v[206:209], v[32:47]
	s_waitcnt lgkmcnt(1)
	v_mfma_f32_32x32x16_bf16 v[16:31], v[0:3], v[194:197], 0
	ds_read_b128 v[0:3], v176 offset:11264
	ds_read_b128 v[214:217], v176 offset:11776
	s_waitcnt lgkmcnt(1)
	v_mfma_f32_32x32x16_bf16 v[16:31], v[0:3], v[198:201], v[16:31]
	ds_read_b128 v[0:3], v176 offset:19456
	ds_read_b128 v[218:221], v176 offset:19968
	s_waitcnt lgkmcnt(1)
	v_mfma_f32_32x32x16_bf16 v[16:31], v[0:3], v[202:205], v[16:31]
	ds_read_b128 v[0:3], v176 offset:27648
	ds_read_b128 v[222:225], v176 offset:28160
	s_waitcnt lgkmcnt(1)
	v_mfma_f32_32x32x16_bf16 v[16:31], v[0:3], v[206:209], v[16:31]
	v_mfma_f32_32x32x16_bf16 v[0:15], v[4:7], v[194:197], 0
	v_mfma_f32_32x32x16_bf16 v[0:15], v[214:217], v[198:201], v[0:15]
	v_mfma_f32_32x32x16_bf16 v[0:15], v[218:221], v[202:205], v[0:15]
	s_waitcnt vmcnt(3)
	ds_write_b128 v210, v[226:229] offset:32768
	s_waitcnt vmcnt(2)
	ds_write_b128 v210, v[230:233] offset:33792
	s_waitcnt vmcnt(1)
	ds_write_b128 v210, v[234:237] offset:34816
	s_waitcnt vmcnt(0)
	ds_write_b128 v210, v[238:241] offset:35840
	s_waitcnt lgkmcnt(0)
	s_barrier
; #define XLAS __attribute__((address_space(3)))
; #define X_LOADK(dc) do { _Pragma("unroll") for (int i_ = 0; i_ < 4; ++i_) st[i_] = *(const u32x4*)(Kg + (dc) * 64 + (size_t)i_ * 64 * 1024); } while (0)
; #define X_LOADV(c)  do { _Pragma("unroll") for (int i_ = 0; i_ < 4; ++i_) st[i_] = *(const u32x4*)(Vg + (size_t)(c) * 64 * 2048 + i_ * 64); } while (0)
; #define X_STOREK(buf) do { _Pragma("unroll") for (int i_ = 0; i_ < 4; ++i_) *(XLAS u32x4*)(lds + (buf) + wid * 4096 + (64 * i_ + lane) * 16) = st[i_]; } while (0)
; #define X_STOREV(buf) do { _Pragma("unroll") for (int i_ = 0; i_ < 4; ++i_) *(XLAS u32x4*)(lds + (buf) + (wid + 8 * i_) * 1024 + lane * 16) = st[i_]; } while (0)
; __device__ __forceinline__ void unit(int b, int h, int qblk, const bf16_t* __restrict__ CQ, const bf16_t* __restrict__ CK, const bf16_t* __restrict__ CVT, bf16_t* __restrict__ CO, XLAS unsigned char* lds, const int wv) {
;     ...
;     for (int dc = 0; dc < 4; ++dc) {
;         const int buf = (dc & 1) ? XB1 : XB0, nbuf = (dc & 1) ? XB0 : XB1;
;         if (dc < 3) X_LOADK(dc + 1); else X_LOADV(0);
; #pragma unroll
;         for (int kt = 0; kt < 8; ++kt)
; #pragma unroll
;             for (int ks = 0; ks < 4; ++ks) {
;                 const bf16x8 kf = *(const XLAS bf16x8*)(lds + buf + koff + kt * 512 + ks * 8192);
;                 s[kt] = __builtin_amdgcn_mfma_f32_32x32x16_bf16(kf, qfa[dc][ks], s[kt], 0, 0, 0);
;             }
;         if (dc < 3) X_STOREK(nbuf); else X_STOREV(nbuf);
;         __syncthreads();
	global_load_dwordx4 v[226:229], v[180:181], off offset:256
	global_load_dwordx4 v[230:233], v[182:183], off offset:256
	global_load_dwordx4 v[234:237], v[184:185], off offset:256
	global_load_dwordx4 v[238:241], v[186:187], off offset:256
	ds_read_b128 v[194:197], v176 offset:32768
	ds_read_b128 v[198:201], v176 offset:33280
	s_waitcnt lgkmcnt(1)
	v_mfma_f32_32x32x16_bf16 v[112:127], v[194:197], v[172:175], v[112:127]
	ds_read_b128 v[194:197], v176 offset:40960
	ds_read_b128 v[202:205], v176 offset:41472
	s_waitcnt lgkmcnt(1)
	v_mfma_f32_32x32x16_bf16 v[112:127], v[194:197], v[168:171], v[112:127]
	v_mfma_f32_32x32x16_bf16 v[0:15], v[222:225], v[206:209], v[0:15]
	ds_read_b128 v[194:197], v176 offset:49152
	ds_read_b128 v[206:209], v176 offset:49664
	s_waitcnt lgkmcnt(1)
	v_mfma_f32_32x32x16_bf16 v[112:127], v[194:197], v[164:167], v[112:127]
	ds_read_b128 v[194:197], v176 offset:57344
	ds_read_b128 v[214:217], v176 offset:57856
	s_waitcnt lgkmcnt(1)
	v_mfma_f32_32x32x16_bf16 v[112:127], v[194:197], v[160:163], v[112:127]
	v_mfma_f32_32x32x16_bf16 v[96:111], v[198:201], v[172:175], v[96:111]
	ds_read_b128 v[194:197], v176 offset:33792
	ds_read_b128 v[198:201], v176 offset:34304
	s_waitcnt lgkmcnt(1)
	v_mfma_f32_32x32x16_bf16 v[80:95], v[194:197], v[172:175], v[80:95]
	v_mfma_f32_32x32x16_bf16 v[96:111], v[202:205], v[168:171], v[96:111]
	ds_read_b128 v[194:197], v176 offset:41984
	ds_read_b128 v[202:205], v176 offset:42496
	s_waitcnt lgkmcnt(1)
	v_mfma_f32_32x32x16_bf16 v[80:95], v[194:197], v[168:171], v[80:95]
	v_mfma_f32_32x32x16_bf16 v[96:111], v[206:209], v[164:167], v[96:111]
	ds_read_b128 v[194:197], v176 offset:50176
	ds_read_b128 v[206:209], v176 offset:50688
	s_waitcnt lgkmcnt(1)
	v_mfma_f32_32x32x16_bf16 v[80:95], v[194:197], v[164:167], v[80:95]
	v_mfma_f32_32x32x16_bf16 v[96:111], v[214:217], v[160:163], v[96:111]
	ds_read_b128 v[194:197], v176 offset:58368
	ds_read_b128 v[214:217], v176 offset:58880
	s_waitcnt lgkmcnt(1)
	v_mfma_f32_32x32x16_bf16 v[80:95], v[194:197], v[160:163], v[80:95]
	v_mfma_f32_32x32x16_bf16 v[64:79], v[198:201], v[172:175], v[64:79]
	ds_read_b128 v[194:197], v176 offset:34816
	ds_read_b128 v[198:201], v176 offset:35328
	s_waitcnt lgkmcnt(1)
	v_mfma_f32_32x32x16_bf16 v[48:63], v[194:197], v[172:175], v[48:63]
	v_mfma_f32_32x32x16_bf16 v[64:79], v[202:205], v[168:171], v[64:79]
	ds_read_b128 v[194:197], v176 offset:43008
	ds_read_b128 v[202:205], v176 offset:43520
	s_waitcnt lgkmcnt(1)
	v_mfma_f32_32x32x16_bf16 v[48:63], v[194:197], v[168:171], v[48:63]
	v_mfma_f32_32x32x16_bf16 v[64:79], v[206:209], v[164:167], v[64:79]
	ds_read_b128 v[194:197], v176 offset:51200
	ds_read_b128 v[206:209], v176 offset:51712
	s_waitcnt lgkmcnt(1)
	v_mfma_f32_32x32x16_bf16 v[48:63], v[194:197], v[164:167], v[48:63]
	v_mfma_f32_32x32x16_bf16 v[64:79], v[214:217], v[160:163], v[64:79]
	ds_read_b128 v[194:197], v176 offset:59392
	ds_read_b128 v[214:217], v176 offset:59904
	s_waitcnt lgkmcnt(1)
	v_mfma_f32_32x32x16_bf16 v[48:63], v[194:197], v[160:163], v[48:63]
	v_mfma_f32_32x32x16_bf16 v[32:47], v[198:201], v[172:175], v[32:47]
	ds_read_b128 v[194:197], v176 offset:35840
	ds_read_b128 v[198:201], v176 offset:36352
	s_waitcnt lgkmcnt(1)
	v_mfma_f32_32x32x16_bf16 v[16:31], v[194:197], v[172:175], v[16:31]
	v_mfma_f32_32x32x16_bf16 v[32:47], v[202:205], v[168:171], v[32:47]
	ds_read_b128 v[194:197], v176 offset:44032
	ds_read_b128 v[202:205], v176 offset:44544
	s_waitcnt lgkmcnt(1)
	v_mfma_f32_32x32x16_bf16 v[16:31], v[194:197], v[168:171], v[16:31]
	v_mfma_f32_32x32x16_bf16 v[32:47], v[206:209], v[164:167], v[32:47]
	ds_read_b128 v[194:197], v176 offset:52224
	ds_read_b128 v[206:209], v176 offset:52736
	s_waitcnt lgkmcnt(1)
	v_mfma_f32_32x32x16_bf16 v[16:31], v[194:197], v[164:167], v[16:31]
	v_mfma_f32_32x32x16_bf16 v[0:15], v[198:201], v[172:175], v[0:15]
	v_mfma_f32_32x32x16_bf16 v[32:47], v[214:217], v[160:163], v[32:47]
	ds_read_b128 v[194:197], v176 offset:60416
	ds_read_b128 v[214:217], v176 offset:60928
	s_waitcnt lgkmcnt(1)
	v_mfma_f32_32x32x16_bf16 v[16:31], v[194:197], v[160:163], v[16:31]
	v_mfma_f32_32x32x16_bf16 v[0:15], v[202:205], v[168:171], v[0:15]
	s_waitcnt vmcnt(3)
	ds_write_b128 v210, v[226:229]
	s_waitcnt vmcnt(2)
	ds_write_b128 v210, v[230:233] offset:1024
	s_waitcnt vmcnt(1)
	ds_write_b128 v210, v[234:237] offset:2048
	s_waitcnt vmcnt(0)
	ds_write_b128 v210, v[238:241] offset:3072
	v_mfma_f32_32x32x16_bf16 v[0:15], v[206:209], v[164:167], v[0:15]
	s_waitcnt lgkmcnt(0)
	s_barrier
; #define XLAS __attribute__((address_space(3)))
; #define X_LOADK(dc) do { _Pragma("unroll") for (int i_ = 0; i_ < 4; ++i_) st[i_] = *(const u32x4*)(Kg + (dc) * 64 + (size_t)i_ * 64 * 1024); } while (0)
; #define X_LOADV(c)  do { _Pragma("unroll") for (int i_ = 0; i_ < 4; ++i_) st[i_] = *(const u32x4*)(Vg + (size_t)(c) * 64 * 2048 + i_ * 64); } while (0)
; #define X_STOREK(buf) do { _Pragma("unroll") for (int i_ = 0; i_ < 4; ++i_) *(XLAS u32x4*)(lds + (buf) + wid * 4096 + (64 * i_ + lane) * 16) = st[i_]; } while (0)
; #define X_STOREV(buf) do { _Pragma("unroll") for (int i_ = 0; i_ < 4; ++i_) *(XLAS u32x4*)(lds + (buf) + (wid + 8 * i_) * 1024 + lane * 16) = st[i_]; } while (0)
; __device__ __forceinline__ void unit(int b, int h, int qblk, const bf16_t* __restrict__ CQ, const bf16_t* __restrict__ CK, const bf16_t* __restrict__ CVT, bf16_t* __restrict__ CO, XLAS unsigned char* lds, const int wv) {
;     ...
;     for (int dc = 0; dc < 4; ++dc) {
;         const int buf = (dc & 1) ? XB1 : XB0, nbuf = (dc & 1) ? XB0 : XB1;
;         if (dc < 3) X_LOADK(dc + 1); else X_LOADV(0);
; #pragma unroll
;         for (int kt = 0; kt < 8; ++kt)
; #pragma unroll
;             for (int ks = 0; ks < 4; ++ks) {
;                 const bf16x8 kf = *(const XLAS bf16x8*)(lds + buf + koff + kt * 512 + ks * 8192);
;                 s[kt] = __builtin_amdgcn_mfma_f32_32x32x16_bf16(kf, qfa[dc][ks], s[kt], 0, 0, 0);
;             }
;         if (dc < 3) X_STOREK(nbuf); else X_STOREV(nbuf);
;         __syncthreads();
	global_load_dwordx4 v[226:229], v[180:181], off offset:384
	global_load_dwordx4 v[230:233], v[182:183], off offset:384
	global_load_dwordx4 v[234:237], v[184:185], off offset:384
	global_load_dwordx4 v[238:241], v[186:187], off offset:384
	v_mfma_f32_32x32x16_bf16 v[0:15], v[214:217], v[160:163], v[0:15]
	ds_read_b128 v[160:163], v176
	ds_read_b128 v[164:167], v176 offset:512
	s_waitcnt lgkmcnt(1)
	v_mfma_f32_32x32x16_bf16 v[112:127], v[160:163], v[156:159], v[112:127]
	ds_read_b128 v[160:163], v176 offset:8192
	ds_read_b128 v[168:171], v176 offset:8704
	s_waitcnt lgkmcnt(1)
	v_mfma_f32_32x32x16_bf16 v[112:127], v[160:163], v[152:155], v[112:127]
	ds_read_b128 v[160:163], v176 offset:16384
	ds_read_b128 v[172:175], v176 offset:16896
	s_waitcnt lgkmcnt(1)
	v_mfma_f32_32x32x16_bf16 v[112:127], v[160:163], v[148:151], v[112:127]
	ds_read_b128 v[160:163], v176 offset:24576
	ds_read_b128 v[194:197], v176 offset:25088
	s_waitcnt lgkmcnt(1)
	v_mfma_f32_32x32x16_bf16 v[112:127], v[160:163], v[144:147], v[112:127]
	v_mfma_f32_32x32x16_bf16 v[96:111], v[164:167], v[156:159], v[96:111]
	ds_read_b128 v[160:163], v176 offset:1024
	ds_read_b128 v[164:167], v176 offset:1536
	s_waitcnt lgkmcnt(1)
	v_mfma_f32_32x32x16_bf16 v[80:95], v[160:163], v[156:159], v[80:95]
	v_mfma_f32_32x32x16_bf16 v[96:111], v[168:171], v[152:155], v[96:111]
	ds_read_b128 v[160:163], v176 offset:9216
	ds_read_b128 v[168:171], v176 offset:9728
	s_waitcnt lgkmcnt(1)
	v_mfma_f32_32x32x16_bf16 v[80:95], v[160:163], v[152:155], v[80:95]
	v_mfma_f32_32x32x16_bf16 v[96:111], v[172:175], v[148:151], v[96:111]
	ds_read_b128 v[160:163], v176 offset:17408
	ds_read_b128 v[172:175], v176 offset:17920
	s_waitcnt lgkmcnt(1)
	v_mfma_f32_32x32x16_bf16 v[80:95], v[160:163], v[148:151], v[80:95]
	v_mfma_f32_32x32x16_bf16 v[96:111], v[194:197], v[144:147], v[96:111]
	ds_read_b128 v[160:163], v176 offset:25600
	ds_read_b128 v[194:197], v176 offset:26112
	s_waitcnt lgkmcnt(1)
	v_mfma_f32_32x32x16_bf16 v[80:95], v[160:163], v[144:147], v[80:95]
	v_mfma_f32_32x32x16_bf16 v[64:79], v[164:167], v[156:159], v[64:79]
	ds_read_b128 v[160:163], v176 offset:2048
	ds_read_b128 v[164:167], v176 offset:2560
	s_waitcnt lgkmcnt(1)
	v_mfma_f32_32x32x16_bf16 v[48:63], v[160:163], v[156:159], v[48:63]
	v_mfma_f32_32x32x16_bf16 v[64:79], v[168:171], v[152:155], v[64:79]
	ds_read_b128 v[160:163], v176 offset:10240
	ds_read_b128 v[168:171], v176 offset:10752
	s_waitcnt lgkmcnt(1)
	v_mfma_f32_32x32x16_bf16 v[48:63], v[160:163], v[152:155], v[48:63]
	v_mfma_f32_32x32x16_bf16 v[64:79], v[172:175], v[148:151], v[64:79]
	ds_read_b128 v[160:163], v176 offset:18432
	ds_read_b128 v[172:175], v176 offset:18944
	s_waitcnt lgkmcnt(1)
	v_mfma_f32_32x32x16_bf16 v[48:63], v[160:163], v[148:151], v[48:63]
	v_mfma_f32_32x32x16_bf16 v[64:79], v[194:197], v[144:147], v[64:79]
	ds_read_b128 v[160:163], v176 offset:26624
	ds_read_b128 v[194:197], v176 offset:27136
	s_waitcnt lgkmcnt(1)
	v_mfma_f32_32x32x16_bf16 v[48:63], v[160:163], v[144:147], v[48:63]
	v_mfma_f32_32x32x16_bf16 v[32:47], v[164:167], v[156:159], v[32:47]
	ds_read_b128 v[160:163], v176 offset:3072
	ds_read_b128 v[164:167], v176 offset:3584
	s_waitcnt lgkmcnt(1)
	v_mfma_f32_32x32x16_bf16 v[16:31], v[160:163], v[156:159], v[16:31]
	v_mfma_f32_32x32x16_bf16 v[32:47], v[168:171], v[152:155], v[32:47]
	ds_read_b128 v[160:163], v176 offset:11264
	ds_read_b128 v[168:171], v176 offset:11776
	s_waitcnt lgkmcnt(1)
	v_mfma_f32_32x32x16_bf16 v[16:31], v[160:163], v[152:155], v[16:31]
	v_mfma_f32_32x32x16_bf16 v[32:47], v[172:175], v[148:151], v[32:47]
	ds_read_b128 v[160:163], v176 offset:19456
	ds_read_b128 v[172:175], v176 offset:19968
	s_waitcnt lgkmcnt(1)
	v_mfma_f32_32x32x16_bf16 v[16:31], v[160:163], v[148:151], v[16:31]
	v_mfma_f32_32x32x16_bf16 v[0:15], v[164:167], v[156:159], v[0:15]
	v_mfma_f32_32x32x16_bf16 v[32:47], v[194:197], v[144:147], v[32:47]
	ds_read_b128 v[160:163], v176 offset:27648
	ds_read_b128 v[194:197], v176 offset:28160
	s_waitcnt lgkmcnt(1)
	v_mfma_f32_32x32x16_bf16 v[16:31], v[160:163], v[144:147], v[16:31]
	v_mfma_f32_32x32x16_bf16 v[0:15], v[168:171], v[152:155], v[0:15]
	s_waitcnt vmcnt(3)
	ds_write_b128 v210, v[226:229] offset:32768
	s_waitcnt vmcnt(2)
	ds_write_b128 v210, v[230:233] offset:33792
	s_waitcnt vmcnt(1)
	ds_write_b128 v210, v[234:237] offset:34816
	s_waitcnt vmcnt(0)
	ds_write_b128 v210, v[238:241] offset:35840
	v_mfma_f32_32x32x16_bf16 v[0:15], v[172:175], v[148:151], v[0:15]
	s_waitcnt lgkmcnt(0)
	s_barrier
; #define XLAS __attribute__((address_space(3)))
; #define X_LOADK(dc) do { _Pragma("unroll") for (int i_ = 0; i_ < 4; ++i_) st[i_] = *(const u32x4*)(Kg + (dc) * 64 + (size_t)i_ * 64 * 1024); } while (0)
; #define X_LOADV(c)  do { _Pragma("unroll") for (int i_ = 0; i_ < 4; ++i_) st[i_] = *(const u32x4*)(Vg + (size_t)(c) * 64 * 2048 + i_ * 64); } while (0)
; #define X_STOREK(buf) do { _Pragma("unroll") for (int i_ = 0; i_ < 4; ++i_) *(XLAS u32x4*)(lds + (buf) + wid * 4096 + (64 * i_ + lane) * 16) = st[i_]; } while (0)
; #define X_STOREV(buf) do { _Pragma("unroll") for (int i_ = 0; i_ < 4; ++i_) *(XLAS u32x4*)(lds + (buf) + (wid + 8 * i_) * 1024 + lane * 16) = st[i_]; } while (0)
; __device__ __forceinline__ void unit(int b, int h, int qblk, const bf16_t* __restrict__ CQ, const bf16_t* __restrict__ CK, const bf16_t* __restrict__ CVT, bf16_t* __restrict__ CO, XLAS unsigned char* lds, const int wv) {
;     ...
;     for (int dc = 0; dc < 4; ++dc) {
;         const int buf = (dc & 1) ? XB1 : XB0, nbuf = (dc & 1) ? XB0 : XB1;
;         if (dc < 3) X_LOADK(dc + 1); else X_LOADV(0);
; #pragma unroll
;         for (int kt = 0; kt < 8; ++kt)
; #pragma unroll
;             for (int ks = 0; ks < 4; ++ks) {
;                 const bf16x8 kf = *(const XLAS bf16x8*)(lds + buf + koff + kt * 512 + ks * 8192);
;                 s[kt] = __builtin_amdgcn_mfma_f32_32x32x16_bf16(kf, qfa[dc][ks], s[kt], 0, 0, 0);
;             }
;         if (dc < 3) X_STOREK(nbuf); else X_STOREV(nbuf);
;         __syncthreads();
;     }
;     float mx = s[0][0];
; #pragma unroll
;     for (int kt = 0; kt < 8; ++kt)
; #pragma unroll
;         for (int r = 0; r < 16; ++r) mx = fmaxf(mx, s[kt][r]);
	v_lshl_add_u64 v[242:243], v[178:179], 0, s[14:15]
	v_lshl_add_u64 v[242:243], v[242:243], 0, s[16:17]
	global_load_dwordx4 v[226:229], v[242:243], off
	global_load_dwordx4 v[230:233], v[242:243], off offset:128
	global_load_dwordx4 v[234:237], v[242:243], off offset:256
	global_load_dwordx4 v[238:241], v[242:243], off offset:384
	v_mfma_f32_32x32x16_bf16 v[0:15], v[194:197], v[144:147], v[0:15]
	ds_read_b128 v[144:147], v176 offset:32768
	ds_read_b128 v[148:151], v176 offset:33280
	s_waitcnt lgkmcnt(1)
	v_mfma_f32_32x32x16_bf16 v[112:127], v[144:147], v[140:143], v[112:127]
	ds_read_b128 v[144:147], v176 offset:40960
	ds_read_b128 v[152:155], v176 offset:41472
	s_waitcnt lgkmcnt(1)
	v_mfma_f32_32x32x16_bf16 v[112:127], v[144:147], v[136:139], v[112:127]
	ds_read_b128 v[144:147], v176 offset:49152
	ds_read_b128 v[156:159], v176 offset:49664
	s_waitcnt lgkmcnt(1)
	v_mfma_f32_32x32x16_bf16 v[112:127], v[144:147], v[132:135], v[112:127]
	ds_read_b128 v[144:147], v176 offset:57344
	ds_read_b128 v[160:163], v176 offset:57856
	s_waitcnt lgkmcnt(1)
	v_mfma_f32_32x32x16_bf16 v[112:127], v[144:147], v[128:131], v[112:127]
	v_mfma_f32_32x32x16_bf16 v[96:111], v[148:151], v[140:143], v[96:111]
	ds_read_b128 v[144:147], v176 offset:33792
	ds_read_b128 v[148:151], v176 offset:34304
	s_waitcnt lgkmcnt(1)
	v_mfma_f32_32x32x16_bf16 v[80:95], v[144:147], v[140:143], v[80:95]
	v_mfma_f32_32x32x16_bf16 v[96:111], v[152:155], v[136:139], v[96:111]
	ds_read_b128 v[144:147], v176 offset:41984
	ds_read_b128 v[152:155], v176 offset:42496
	s_waitcnt lgkmcnt(1)
	v_mfma_f32_32x32x16_bf16 v[80:95], v[144:147], v[136:139], v[80:95]
	v_mfma_f32_32x32x16_bf16 v[96:111], v[156:159], v[132:135], v[96:111]
	ds_read_b128 v[144:147], v176 offset:50176
	ds_read_b128 v[156:159], v176 offset:50688
	s_waitcnt lgkmcnt(1)
	v_mfma_f32_32x32x16_bf16 v[80:95], v[144:147], v[132:135], v[80:95]
	v_mfma_f32_32x32x16_bf16 v[96:111], v[160:163], v[128:131], v[96:111]
	ds_read_b128 v[144:147], v176 offset:58368
	ds_read_b128 v[160:163], v176 offset:58880
	s_waitcnt lgkmcnt(1)
	v_mfma_f32_32x32x16_bf16 v[80:95], v[144:147], v[128:131], v[80:95]
	v_mfma_f32_32x32x16_bf16 v[64:79], v[148:151], v[140:143], v[64:79]
	ds_read_b128 v[144:147], v176 offset:34816
	ds_read_b128 v[148:151], v176 offset:35328
	s_waitcnt lgkmcnt(1)
	v_mfma_f32_32x32x16_bf16 v[48:63], v[144:147], v[140:143], v[48:63]
	v_mfma_f32_32x32x16_bf16 v[64:79], v[152:155], v[136:139], v[64:79]
	ds_read_b128 v[144:147], v176 offset:43008
	ds_read_b128 v[152:155], v176 offset:43520
	s_waitcnt lgkmcnt(1)
	v_mfma_f32_32x32x16_bf16 v[48:63], v[144:147], v[136:139], v[48:63]
	v_mfma_f32_32x32x16_bf16 v[64:79], v[156:159], v[132:135], v[64:79]
	ds_read_b128 v[144:147], v176 offset:51200
	ds_read_b128 v[156:159], v176 offset:51712
	s_waitcnt lgkmcnt(1)
	v_mfma_f32_32x32x16_bf16 v[48:63], v[144:147], v[132:135], v[48:63]
	v_mfma_f32_32x32x16_bf16 v[64:79], v[160:163], v[128:131], v[64:79]
	ds_read_b128 v[144:147], v176 offset:59392
	ds_read_b128 v[160:163], v176 offset:59904
	s_waitcnt lgkmcnt(1)
	v_mfma_f32_32x32x16_bf16 v[48:63], v[144:147], v[128:131], v[48:63]
	v_lshl_add_u64 v[144:145], v[178:179], 0, s[14:15]
	v_lshl_add_u64 v[144:145], v[144:145], 0, s[16:17]
	s_lshl_b32 s14, s29, 10
	s_add_i32 s14, s14, 0
	v_add_u32_e32 v146, s14, v193
	v_max_f32_e32 v147, v113, v113
	v_mfma_f32_32x32x16_bf16 v[32:47], v[148:151], v[140:143], v[32:47]
	s_and_b32 s14, s27, 0x3fffffc0
	s_lshl_b32 s14, s14, 2
	s_add_i32 s17, s14, 0
	s_lshl_b32 s16, s28, 8
	s_add_i32 s17, s17, 0x10000
	v_mfma_f32_32x32x16_bf16 v[32:47], v[152:155], v[136:139], v[32:47]
	ds_read_b128 v[172:175], v176 offset:35840
	ds_read_b128 v[178:181], v176 offset:36352
	ds_read_b128 v[182:185], v176 offset:44032
	ds_read_b128 v[194:197], v176 offset:44544
	ds_read_b128 v[198:201], v176 offset:52224
	ds_read_b128 v[202:205], v176 offset:52736
	v_mfma_f32_32x32x16_bf16 v[32:47], v[156:159], v[132:135], v[32:47]
	ds_read_b128 v[156:159], v176 offset:60416
	ds_read_b128 v[206:209], v176 offset:60928
	s_waitcnt vmcnt(3)
	ds_write_b128 v146, v[226:229]
	s_waitcnt vmcnt(2)
	ds_write_b128 v146, v[230:233] offset:8192
	s_waitcnt vmcnt(1)
	ds_write_b128 v146, v[234:237] offset:16384
	v_max_f32_e32 v148, v112, v112
	v_max_f32_e32 v147, v148, v147
	v_max3_f32 v147, v147, v114, v115
	v_max3_f32 v147, v147, v116, v117
	v_max3_f32 v147, v147, v118, v119
	v_max3_f32 v147, v147, v120, v121
	v_max3_f32 v147, v147, v122, v123
	v_max3_f32 v147, v147, v124, v125
	v_max3_f32 v147, v147, v126, v127
	v_max3_f32 v147, v147, v96, v97
	v_max3_f32 v147, v147, v98, v99
	v_max3_f32 v147, v147, v100, v101
	v_max3_f32 v147, v147, v102, v103
	v_max3_f32 v147, v147, v104, v105
	v_max3_f32 v147, v147, v106, v107
	v_max3_f32 v147, v147, v108, v109
	v_max3_f32 v147, v147, v110, v111
	s_waitcnt lgkmcnt(10)
	v_mfma_f32_32x32x16_bf16 v[16:31], v[172:175], v[140:143], v[16:31]
	v_max3_f32 v147, v147, v80, v81
	v_max3_f32 v147, v147, v82, v83
	v_max3_f32 v147, v147, v84, v85
	v_max3_f32 v147, v147, v86, v87
	v_max3_f32 v147, v147, v88, v89
	v_max3_f32 v147, v147, v90, v91
	v_max3_f32 v147, v147, v92, v93
	v_max3_f32 v147, v147, v94, v95
	s_waitcnt lgkmcnt(8)
	v_mfma_f32_32x32x16_bf16 v[16:31], v[182:185], v[136:139], v[16:31]
	v_max3_f32 v147, v147, v64, v65
	v_max3_f32 v147, v147, v66, v67
	v_max3_f32 v147, v147, v68, v69
	v_max3_f32 v147, v147, v70, v71
	v_max3_f32 v147, v147, v72, v73
	v_max3_f32 v147, v147, v74, v75
	v_max3_f32 v147, v147, v76, v77
	v_mfma_f32_32x32x16_bf16 v[0:15], v[178:181], v[140:143], v[0:15]
	v_max3_f32 v147, v147, v78, v79
	v_max3_f32 v147, v147, v48, v49
	v_max3_f32 v147, v147, v50, v51
	v_max3_f32 v147, v147, v52, v53
	v_max3_f32 v140, v147, v54, v55
	v_max3_f32 v140, v140, v56, v57
	v_max3_f32 v140, v140, v58, v59
	v_mfma_f32_32x32x16_bf16 v[32:47], v[160:163], v[128:131], v[32:47]
	v_max3_f32 v140, v140, v60, v61
	v_max3_f32 v140, v140, v62, v63
	s_waitcnt vmcnt(0)
	ds_write_b128 v146, v[238:241] offset:24576
	s_waitcnt lgkmcnt(0)
	s_barrier
; __device__ __forceinline__ void unit(int b, int h, int qblk, const bf16_t* __restrict__ CQ, const bf16_t* __restrict__ CK, const bf16_t* __restrict__ CVT, bf16_t* __restrict__ CO, XLAS unsigned char* lds, const int wv) {
;     ...
;     float mx = s[0][0];
; #pragma unroll
;     for (int kt = 0; kt < 8; ++kt)
; #pragma unroll
;         for (int r = 0; r < 16; ++r) mx = fmaxf(mx, s[kt][r]);
;     mx = fmaxf(mx, __shfl_xor(mx, 32));
;     float l = 0.f;
; #pragma unroll
;     for (int kt = 0; kt < 8; ++kt)
; #pragma unroll
;         for (int r = 0; r < 16; ++r) { const float p = __builtin_amdgcn_exp2f(s[kt][r] - mx); s[kt][r] = p; l += p; }
	s_nop 5
	v_max3_f32 v140, v140, v32, v33
	v_mfma_f32_32x32x16_bf16 v[16:31], v[198:201], v[132:135], v[16:31]
	v_max3_f32 v140, v140, v34, v35
	v_mfma_f32_32x32x16_bf16 v[0:15], v[194:197], v[136:139], v[0:15]
	v_max3_f32 v136, v140, v36, v37
	v_max3_f32 v136, v136, v38, v39
	v_max3_f32 v136, v136, v40, v41
	v_max3_f32 v136, v136, v42, v43
	v_max3_f32 v136, v136, v44, v45
	v_max3_f32 v136, v136, v46, v47
	v_mfma_f32_32x32x16_bf16 v[16:31], v[156:159], v[128:131], v[16:31]
	v_mfma_f32_32x32x16_bf16 v[0:15], v[202:205], v[132:135], v[0:15]
	s_nop 10
	v_max3_f32 v136, v136, v16, v17
	v_max3_f32 v132, v136, v18, v19
	v_max3_f32 v132, v132, v20, v21
	v_max3_f32 v132, v132, v22, v23
	v_max3_f32 v132, v132, v24, v25
	v_max3_f32 v132, v132, v26, v27
	v_max3_f32 v132, v132, v28, v29
	v_mfma_f32_32x32x16_bf16 v[0:15], v[206:209], v[128:131], v[0:15]
	v_max3_f32 v132, v132, v30, v31
	s_nop 10
	v_max3_f32 v128, v132, v0, v1
	v_max3_f32 v128, v128, v2, v3
	v_max3_f32 v128, v128, v4, v5
	v_max3_f32 v128, v128, v6, v7
	v_max3_f32 v128, v128, v8, v9
	v_max3_f32 v128, v128, v10, v11
	v_max3_f32 v128, v128, v12, v13
	v_max3_f32 v128, v128, v14, v15
	ds_bpermute_b32 v129, v188, v128
	s_waitcnt lgkmcnt(0)
	v_max_f32_e32 v129, v129, v129
	v_max_f32_e32 v128, v128, v129
	v_sub_f32_e32 v112, v112, v128
	v_exp_f32_e32 v112, v112
	v_sub_f32_e32 v113, v113, v128
	v_exp_f32_e32 v113, v113
	v_sub_f32_e32 v114, v114, v128
	v_exp_f32_e32 v114, v114
	v_sub_f32_e32 v115, v115, v128
	v_exp_f32_e32 v115, v115
	v_sub_f32_e32 v116, v116, v128
	v_add_f32_e32 v129, 0, v112
	v_exp_f32_e32 v116, v116
	v_sub_f32_e32 v117, v117, v128
	v_add_f32_e32 v129, v113, v129
	v_exp_f32_e32 v117, v117
	v_sub_f32_e32 v118, v118, v128
	v_add_f32_e32 v129, v114, v129
	v_exp_f32_e32 v118, v118
	v_sub_f32_e32 v119, v119, v128
	v_add_f32_e32 v129, v115, v129
	v_exp_f32_e32 v119, v119
	v_sub_f32_e32 v120, v120, v128
	v_add_f32_e32 v129, v116, v129
	v_exp_f32_e32 v120, v120
	v_sub_f32_e32 v121, v121, v128
	v_add_f32_e32 v129, v117, v129
	v_exp_f32_e32 v121, v121
	v_sub_f32_e32 v122, v122, v128
	v_add_f32_e32 v129, v118, v129
	v_exp_f32_e32 v122, v122
	v_sub_f32_e32 v123, v123, v128
	v_add_f32_e32 v129, v119, v129
	v_exp_f32_e32 v123, v123
	v_sub_f32_e32 v124, v124, v128
	v_add_f32_e32 v129, v120, v129
	v_exp_f32_e32 v124, v124
	v_sub_f32_e32 v125, v125, v128
	v_add_f32_e32 v129, v121, v129
	v_exp_f32_e32 v125, v125
	v_sub_f32_e32 v126, v126, v128
	v_add_f32_e32 v129, v122, v129
	v_exp_f32_e32 v126, v126
	v_sub_f32_e32 v127, v127, v128
	v_add_f32_e32 v129, v123, v129
	v_exp_f32_e32 v127, v127
	v_sub_f32_e32 v96, v96, v128
	v_add_f32_e32 v129, v124, v129
	v_exp_f32_e32 v96, v96
	v_sub_f32_e32 v97, v97, v128
	v_add_f32_e32 v129, v125, v129
	v_exp_f32_e32 v97, v97
	v_sub_f32_e32 v98, v98, v128
	v_add_f32_e32 v129, v126, v129
	v_exp_f32_e32 v98, v98
	v_sub_f32_e32 v99, v99, v128
	v_add_f32_e32 v129, v127, v129
	v_exp_f32_e32 v99, v99
	v_sub_f32_e32 v100, v100, v128
	v_add_f32_e32 v129, v96, v129
	v_exp_f32_e32 v100, v100
	v_sub_f32_e32 v101, v101, v128
	v_add_f32_e32 v129, v97, v129
	v_exp_f32_e32 v101, v101
	v_sub_f32_e32 v102, v102, v128
	v_add_f32_e32 v129, v98, v129
	v_exp_f32_e32 v102, v102
	v_sub_f32_e32 v103, v103, v128
	v_add_f32_e32 v129, v99, v129
	v_exp_f32_e32 v103, v103
	v_sub_f32_e32 v104, v104, v128
	v_add_f32_e32 v129, v100, v129
	v_exp_f32_e32 v104, v104
	v_sub_f32_e32 v105, v105, v128
	v_add_f32_e32 v129, v101, v129
	v_exp_f32_e32 v105, v105
	v_sub_f32_e32 v106, v106, v128
	v_add_f32_e32 v129, v102, v129
	v_exp_f32_e32 v106, v106
	v_sub_f32_e32 v107, v107, v128
	v_add_f32_e32 v129, v103, v129
	v_exp_f32_e32 v107, v107
	v_sub_f32_e32 v108, v108, v128
	v_add_f32_e32 v129, v104, v129
	v_exp_f32_e32 v108, v108
	v_sub_f32_e32 v109, v109, v128
	v_add_f32_e32 v129, v105, v129
	v_exp_f32_e32 v109, v109
	v_sub_f32_e32 v110, v110, v128
	v_add_f32_e32 v129, v106, v129
	v_exp_f32_e32 v110, v110
	v_sub_f32_e32 v111, v111, v128
	v_add_f32_e32 v129, v107, v129
	v_exp_f32_e32 v111, v111
	v_sub_f32_e32 v80, v80, v128
	v_add_f32_e32 v129, v108, v129
	v_exp_f32_e32 v130, v80
	v_sub_f32_e32 v80, v81, v128
	v_add_f32_e32 v129, v109, v129
	v_exp_f32_e32 v131, v80
	v_sub_f32_e32 v80, v82, v128
	v_add_f32_e32 v129, v110, v129
	v_exp_f32_e32 v132, v80
	v_sub_f32_e32 v80, v83, v128
	v_add_f32_e32 v129, v111, v129
	v_exp_f32_e32 v133, v80
	v_sub_f32_e32 v81, v84, v128
	v_add_f32_e32 v80, v130, v129
	v_exp_f32_e32 v129, v81
	v_sub_f32_e32 v81, v85, v128
	v_add_f32_e32 v80, v131, v80
	v_exp_f32_e32 v134, v81
	v_sub_f32_e32 v81, v86, v128
	v_add_f32_e32 v80, v132, v80
	v_exp_f32_e32 v135, v81
	v_sub_f32_e32 v81, v87, v128
	v_add_f32_e32 v80, v133, v80
	v_exp_f32_e32 v136, v81
	v_sub_f32_e32 v81, v88, v128
	v_add_f32_e32 v80, v129, v80
	v_exp_f32_e32 v137, v81
	v_sub_f32_e32 v81, v89, v128
	v_add_f32_e32 v80, v134, v80
	v_exp_f32_e32 v138, v81
	v_sub_f32_e32 v81, v90, v128
	v_add_f32_e32 v80, v135, v80
	v_exp_f32_e32 v139, v81
	v_sub_f32_e32 v81, v91, v128
	v_add_f32_e32 v80, v136, v80
	v_exp_f32_e32 v140, v81
	v_sub_f32_e32 v81, v92, v128
	v_add_f32_e32 v80, v137, v80
	v_exp_f32_e32 v141, v81
	v_sub_f32_e32 v81, v93, v128
	v_add_f32_e32 v80, v138, v80
	v_exp_f32_e32 v142, v81
	v_sub_f32_e32 v81, v94, v128
	v_add_f32_e32 v80, v139, v80
	v_exp_f32_e32 v143, v81
	v_sub_f32_e32 v81, v95, v128
	v_add_f32_e32 v80, v140, v80
	v_exp_f32_e32 v147, v81
	v_sub_f32_e32 v64, v64, v128
	v_add_f32_e32 v80, v141, v80
	v_exp_f32_e32 v64, v64
	v_sub_f32_e32 v65, v65, v128
	v_add_f32_e32 v80, v142, v80
	v_exp_f32_e32 v65, v65
	v_sub_f32_e32 v66, v66, v128
	v_add_f32_e32 v80, v143, v80
	v_exp_f32_e32 v66, v66
	v_sub_f32_e32 v67, v67, v128
; __device__ __forceinline__ void unit(int b, int h, int qblk, const bf16_t* __restrict__ CQ, const bf16_t* __restrict__ CK, const bf16_t* __restrict__ CVT, bf16_t* __restrict__ CO, XLAS unsigned char* lds, const int wv) {
;     ...
;     for (int kt = 0; kt < 8; ++kt)
; #pragma unroll
;         for (int r = 0; r < 16; ++r) { const float p = __builtin_amdgcn_exp2f(s[kt][r] - mx); s[kt][r] = p; l += p; }
	v_add_f32_e32 v80, v147, v80
	v_exp_f32_e32 v67, v67
	v_sub_f32_e32 v68, v68, v128
	v_add_f32_e32 v80, v64, v80
	v_exp_f32_e32 v148, v68
	v_sub_f32_e32 v68, v69, v128
	v_add_f32_e32 v80, v65, v80
	v_exp_f32_e32 v149, v68
	v_sub_f32_e32 v68, v70, v128
	v_add_f32_e32 v80, v66, v80
	v_exp_f32_e32 v150, v68
	v_sub_f32_e32 v68, v71, v128
	v_add_f32_e32 v80, v67, v80
	v_exp_f32_e32 v71, v68
	v_sub_f32_e32 v69, v72, v128
	v_add_f32_e32 v68, v148, v80
	v_exp_f32_e32 v151, v69
	v_sub_f32_e32 v69, v73, v128
	v_add_f32_e32 v68, v149, v68
	v_exp_f32_e32 v152, v69
	v_sub_f32_e32 v69, v74, v128
	v_add_f32_e32 v68, v150, v68
	v_exp_f32_e32 v153, v69
	v_sub_f32_e32 v69, v75, v128
	v_add_f32_e32 v68, v71, v68
	v_exp_f32_e32 v154, v69
	v_sub_f32_e32 v69, v76, v128
	v_add_f32_e32 v68, v151, v68
	v_exp_f32_e32 v155, v69
	v_sub_f32_e32 v69, v77, v128
	v_add_f32_e32 v68, v152, v68
	v_exp_f32_e32 v156, v69
	v_sub_f32_e32 v69, v78, v128
	v_add_f32_e32 v68, v153, v68
	v_exp_f32_e32 v157, v69
	v_sub_f32_e32 v69, v79, v128
	v_add_f32_e32 v68, v154, v68
	v_exp_f32_e32 v158, v69
	v_sub_f32_e32 v48, v48, v128
	v_add_f32_e32 v68, v155, v68
	v_exp_f32_e32 v48, v48
	v_sub_f32_e32 v49, v49, v128
	v_add_f32_e32 v68, v156, v68
	v_exp_f32_e32 v49, v49
	v_sub_f32_e32 v50, v50, v128
	v_add_f32_e32 v68, v157, v68
	v_exp_f32_e32 v50, v50
	v_sub_f32_e32 v51, v51, v128
	v_add_f32_e32 v68, v158, v68
	v_exp_f32_e32 v51, v51
	v_sub_f32_e32 v52, v52, v128
	v_add_f32_e32 v68, v48, v68
	v_exp_f32_e32 v52, v52
	v_sub_f32_e32 v53, v53, v128
	v_add_f32_e32 v68, v49, v68
	v_exp_f32_e32 v53, v53
	v_sub_f32_e32 v54, v54, v128
	v_add_f32_e32 v68, v50, v68
	v_exp_f32_e32 v54, v54
	v_sub_f32_e32 v55, v55, v128
	v_add_f32_e32 v68, v51, v68
	v_exp_f32_e32 v55, v55
	v_sub_f32_e32 v56, v56, v128
	v_add_f32_e32 v68, v52, v68
	v_exp_f32_e32 v56, v56
	v_sub_f32_e32 v57, v57, v128
	v_add_f32_e32 v68, v53, v68
	v_exp_f32_e32 v57, v57
	v_sub_f32_e32 v58, v58, v128
	v_add_f32_e32 v68, v54, v68
	v_exp_f32_e32 v58, v58
	v_sub_f32_e32 v59, v59, v128
	v_add_f32_e32 v68, v55, v68
	v_exp_f32_e32 v59, v59
	v_sub_f32_e32 v60, v60, v128
	v_add_f32_e32 v68, v56, v68
	v_exp_f32_e32 v159, v60
	v_sub_f32_e32 v60, v61, v128
	v_add_f32_e32 v68, v57, v68
	v_exp_f32_e32 v160, v60
	v_sub_f32_e32 v60, v62, v128
	v_add_f32_e32 v68, v58, v68
	v_exp_f32_e32 v161, v60
	v_sub_f32_e32 v60, v63, v128
	v_add_f32_e32 v68, v59, v68
	v_exp_f32_e32 v162, v60
	v_sub_f32_e32 v32, v32, v128
	v_add_f32_e32 v60, v159, v68
	v_exp_f32_e32 v32, v32
	v_sub_f32_e32 v33, v33, v128
	v_add_f32_e32 v60, v160, v60
	v_exp_f32_e32 v33, v33
	v_sub_f32_e32 v34, v34, v128
	v_add_f32_e32 v60, v161, v60
	v_exp_f32_e32 v34, v34
	v_sub_f32_e32 v35, v35, v128
	v_add_f32_e32 v60, v162, v60
	v_exp_f32_e32 v35, v35
	v_sub_f32_e32 v36, v36, v128
	v_add_f32_e32 v60, v32, v60
	v_exp_f32_e32 v36, v36
	v_sub_f32_e32 v37, v37, v128
	v_add_f32_e32 v60, v33, v60
	v_exp_f32_e32 v37, v37
	v_sub_f32_e32 v38, v38, v128
	v_add_f32_e32 v60, v34, v60
	v_exp_f32_e32 v38, v38
	v_sub_f32_e32 v39, v39, v128
	v_add_f32_e32 v60, v35, v60
	v_exp_f32_e32 v39, v39
	v_sub_f32_e32 v40, v40, v128
	v_add_f32_e32 v60, v36, v60
	v_exp_f32_e32 v40, v40
	v_sub_f32_e32 v41, v41, v128
	v_add_f32_e32 v60, v37, v60
	v_exp_f32_e32 v41, v41
	v_sub_f32_e32 v42, v42, v128
	v_add_f32_e32 v60, v38, v60
	v_exp_f32_e32 v42, v42
	v_sub_f32_e32 v43, v43, v128
	v_add_f32_e32 v60, v39, v60
	v_exp_f32_e32 v43, v43
	v_sub_f32_e32 v44, v44, v128
	v_add_f32_e32 v60, v40, v60
	v_exp_f32_e32 v44, v44
	v_sub_f32_e32 v45, v45, v128
	v_add_f32_e32 v60, v41, v60
	v_exp_f32_e32 v45, v45
	v_sub_f32_e32 v46, v46, v128
	v_add_f32_e32 v60, v42, v60
	v_exp_f32_e32 v46, v46
	v_sub_f32_e32 v47, v47, v128
	v_add_f32_e32 v60, v43, v60
	v_exp_f32_e32 v47, v47
	v_sub_f32_e32 v16, v16, v128
	v_add_f32_e32 v60, v44, v60
	v_exp_f32_e32 v16, v16
	v_sub_f32_e32 v17, v17, v128
	v_add_f32_e32 v60, v45, v60
	v_exp_f32_e32 v17, v17
	v_sub_f32_e32 v18, v18, v128
	v_add_f32_e32 v60, v46, v60
	v_exp_f32_e32 v18, v18
	v_sub_f32_e32 v19, v19, v128
	v_add_f32_e32 v60, v47, v60
	v_exp_f32_e32 v19, v19
	v_sub_f32_e32 v20, v20, v128
	v_add_f32_e32 v60, v16, v60
	v_exp_f32_e32 v20, v20
	v_sub_f32_e32 v21, v21, v128
	v_add_f32_e32 v60, v17, v60
	v_exp_f32_e32 v21, v21
	v_sub_f32_e32 v22, v22, v128
	v_add_f32_e32 v60, v18, v60
	v_exp_f32_e32 v22, v22
	v_sub_f32_e32 v23, v23, v128
	v_add_f32_e32 v60, v19, v60
	v_exp_f32_e32 v23, v23
; #define XLAS __attribute__((address_space(3)))
; __device__ __forceinline__ unsigned pk(float lo, float hi) { return pg8::cvt_pk_bf16(lo, hi); }
; __device__ __forceinline__ void unit(int b, int h, int qblk, const bf16_t* __restrict__ CQ, const bf16_t* __restrict__ CK, const bf16_t* __restrict__ CVT, bf16_t* __restrict__ CO, XLAS unsigned char* lds, const int wv) {
;     ...
;     for (int kt = 0; kt < 8; ++kt)
; #pragma unroll
;         for (int r = 0; r < 16; ++r) { const float p = __builtin_amdgcn_exp2f(s[kt][r] - mx); s[kt][r] = p; l += p; }
;     l += __shfl_xor(l, 32);
;     u32x4 pw[16];
; #pragma unroll
;     for (int kt = 0; kt < 8; ++kt)
; #pragma unroll
;         for (int j2 = 0; j2 < 2; ++j2)
;             pw[2 * kt + j2] = (u32x4){pk(s[kt][8 * j2 + 0], s[kt][8 * j2 + 1]), pk(s[kt][8 * j2 + 2], s[kt][8 * j2 + 3]), pk(s[kt][8 * j2 + 4], s[kt][8 * j2 + 5]), pk(s[kt][8 * j2 + 6], s[kt][8 * j2 + 7])};
;     XLAS float* wsf = (XLAS float*)(lds + X_WSF) + wid * 64;
;     if (hi == 0) wsf[r32] = l;
	v_sub_f32_e32 v24, v24, v128
	v_add_f32_e32 v60, v20, v60
	v_exp_f32_e32 v24, v24
	v_sub_f32_e32 v25, v25, v128
	v_add_f32_e32 v60, v21, v60
	v_exp_f32_e32 v25, v25
	v_sub_f32_e32 v26, v26, v128
	v_add_f32_e32 v60, v22, v60
	v_exp_f32_e32 v26, v26
	v_sub_f32_e32 v27, v27, v128
	v_add_f32_e32 v60, v23, v60
	v_exp_f32_e32 v27, v27
	v_sub_f32_e32 v28, v28, v128
	v_add_f32_e32 v60, v24, v60
	v_exp_f32_e32 v28, v28
	v_sub_f32_e32 v29, v29, v128
	v_add_f32_e32 v60, v25, v60
	v_exp_f32_e32 v29, v29
	v_sub_f32_e32 v30, v30, v128
	v_add_f32_e32 v60, v26, v60
	v_exp_f32_e32 v30, v30
	v_sub_f32_e32 v31, v31, v128
	v_add_f32_e32 v60, v27, v60
	v_exp_f32_e32 v31, v31
	v_sub_f32_e32 v0, v0, v128
	v_add_f32_e32 v60, v28, v60
	v_exp_f32_e32 v163, v0
	v_sub_f32_e32 v0, v1, v128
	v_add_f32_e32 v60, v29, v60
	v_exp_f32_e32 v164, v0
	v_sub_f32_e32 v0, v2, v128
	v_add_f32_e32 v60, v30, v60
	v_exp_f32_e32 v2, v0
	v_sub_f32_e32 v0, v3, v128
	v_add_f32_e32 v60, v31, v60
	v_exp_f32_e32 v3, v0
	v_sub_f32_e32 v1, v4, v128
	v_add_f32_e32 v0, v163, v60
	v_exp_f32_e32 v4, v1
	v_sub_f32_e32 v1, v5, v128
	v_add_f32_e32 v0, v164, v0
	v_exp_f32_e32 v5, v1
	v_sub_f32_e32 v1, v6, v128
	v_add_f32_e32 v0, v2, v0
	v_exp_f32_e32 v6, v1
	v_sub_f32_e32 v1, v7, v128
	v_add_f32_e32 v0, v3, v0
	v_exp_f32_e32 v7, v1
	v_sub_f32_e32 v1, v8, v128
	v_add_f32_e32 v0, v4, v0
	v_exp_f32_e32 v8, v1
	v_sub_f32_e32 v1, v9, v128
	v_add_f32_e32 v0, v5, v0
	v_exp_f32_e32 v9, v1
	v_sub_f32_e32 v1, v10, v128
	v_add_f32_e32 v0, v6, v0
	v_exp_f32_e32 v10, v1
	v_sub_f32_e32 v1, v11, v128
	v_add_f32_e32 v0, v7, v0
	v_exp_f32_e32 v11, v1
	v_sub_f32_e32 v1, v12, v128
	v_add_f32_e32 v0, v8, v0
	v_exp_f32_e32 v12, v1
	v_sub_f32_e32 v1, v13, v128
	v_add_f32_e32 v0, v9, v0
	v_exp_f32_e32 v13, v1
	v_sub_f32_e32 v1, v14, v128
	v_add_f32_e32 v0, v10, v0
	v_exp_f32_e32 v14, v1
	v_sub_f32_e32 v1, v15, v128
	v_add_f32_e32 v0, v11, v0
	v_exp_f32_e32 v15, v1
	v_add_f32_e32 v0, v12, v0
	v_add_f32_e32 v0, v13, v0
	v_add_f32_e32 v0, v14, v0
	v_add_f32_e32 v0, v15, v0
	ds_bpermute_b32 v1, v188, v0
	v_cvt_pk_bf16_f32 v92, v112, v113
	v_cvt_pk_bf16_f32 v93, v114, v115
	v_cvt_pk_bf16_f32 v94, v116, v117
	v_cvt_pk_bf16_f32 v95, v118, v119
	v_cvt_pk_bf16_f32 v88, v120, v121
	v_cvt_pk_bf16_f32 v89, v122, v123
	v_cvt_pk_bf16_f32 v90, v124, v125
	v_cvt_pk_bf16_f32 v91, v126, v127
	v_cvt_pk_bf16_f32 v84, v96, v97
	v_cvt_pk_bf16_f32 v85, v98, v99
	v_cvt_pk_bf16_f32 v86, v100, v101
	v_cvt_pk_bf16_f32 v87, v102, v103
	v_cvt_pk_bf16_f32 v80, v104, v105
	v_cvt_pk_bf16_f32 v81, v106, v107
	v_cvt_pk_bf16_f32 v82, v108, v109
	v_cvt_pk_bf16_f32 v83, v110, v111
	v_cvt_pk_bf16_f32 v76, v130, v131
	v_cvt_pk_bf16_f32 v77, v132, v133
	v_cvt_pk_bf16_f32 v78, v129, v134
	v_cvt_pk_bf16_f32 v79, v135, v136
	v_cvt_pk_bf16_f32 v72, v137, v138
	v_cvt_pk_bf16_f32 v73, v139, v140
	v_cvt_pk_bf16_f32 v74, v141, v142
	v_cvt_pk_bf16_f32 v75, v143, v147
	v_cvt_pk_bf16_f32 v68, v64, v65
	v_cvt_pk_bf16_f32 v69, v66, v67
	v_cvt_pk_bf16_f32 v70, v148, v149
	v_cvt_pk_bf16_f32 v71, v150, v71
	v_cvt_pk_bf16_f32 v64, v151, v152
	v_cvt_pk_bf16_f32 v65, v153, v154
	v_cvt_pk_bf16_f32 v66, v155, v156
	v_cvt_pk_bf16_f32 v67, v157, v158
	v_cvt_pk_bf16_f32 v60, v48, v49
	v_cvt_pk_bf16_f32 v61, v50, v51
	v_cvt_pk_bf16_f32 v62, v52, v53
	v_cvt_pk_bf16_f32 v63, v54, v55
	v_cvt_pk_bf16_f32 v56, v56, v57
	v_cvt_pk_bf16_f32 v57, v58, v59
	v_cvt_pk_bf16_f32 v58, v159, v160
	v_cvt_pk_bf16_f32 v59, v161, v162
	v_cvt_pk_bf16_f32 v52, v32, v33
	v_cvt_pk_bf16_f32 v53, v34, v35
	v_cvt_pk_bf16_f32 v54, v36, v37
	v_cvt_pk_bf16_f32 v55, v38, v39
	v_cvt_pk_bf16_f32 v48, v40, v41
	v_cvt_pk_bf16_f32 v49, v42, v43
	v_cvt_pk_bf16_f32 v50, v44, v45
	v_cvt_pk_bf16_f32 v51, v46, v47
	v_cvt_pk_bf16_f32 v44, v16, v17
	v_cvt_pk_bf16_f32 v45, v18, v19
	v_cvt_pk_bf16_f32 v46, v20, v21
	v_cvt_pk_bf16_f32 v47, v22, v23
	v_cvt_pk_bf16_f32 v40, v24, v25
	v_cvt_pk_bf16_f32 v41, v26, v27
	v_cvt_pk_bf16_f32 v42, v28, v29
	v_cvt_pk_bf16_f32 v43, v30, v31
	v_cvt_pk_bf16_f32 v36, v163, v164
	v_cvt_pk_bf16_f32 v37, v2, v3
	v_cvt_pk_bf16_f32 v38, v4, v5
	v_cvt_pk_bf16_f32 v39, v6, v7
	v_cvt_pk_bf16_f32 v32, v8, v9
	v_cvt_pk_bf16_f32 v33, v10, v11
	v_cvt_pk_bf16_f32 v34, v12, v13
	v_cvt_pk_bf16_f32 v35, v14, v15
	s_and_saveexec_b64 s[14:15], vcc
	s_cbranch_execz .LBB0_1144
	v_lshl_add_u32 v2, v191, 2, s17
	s_waitcnt lgkmcnt(0)
	v_add_f32_e32 v0, v0, v1
	ds_write_b32 v2, v0
	s_branch .LBB0_1144
